# cross-attention: both 128-query halves fused into one pass over K/V (32 queries per wave, each LDS K/V fragment feeds two MFMAs)
# speedup vs baseline: 1.0120x; 1.0120x over previous
.LBB0_318:
	s_or_b64 exec, exec, s[6:7]
	s_lshl_b32 s6, s52, 7
	s_add_u32 s6, s71, s6
	s_waitcnt lgkmcnt(0)
	s_barrier
	s_addc_u32 s7, s72, 0
	v_lshlrev_b32_e32 v1, 5, v144
	global_load_dwordx4 v[136:139], v1, s[6:7] offset:16
	global_load_dwordx4 v[144:147], v1, s[6:7]
	s_waitcnt lgkmcnt(0)
	global_load_dwordx4 v[132:135], v1, s[6:7] offset:528
	global_load_dwordx4 v[140:143], v1, s[6:7] offset:512
	s_lshl_b32 s6, s55, 10
	s_add_i32 s6, s6, 0
	v_lshl_add_u32 v3, v3, 4, s6
	v_add_u32_e32 v1, 0x20000, v3
	ds_read_b128 v[154:157], v1
	s_lshl_b32 s8, s52, 6
	s_add_i32 s15, s8, 0
	s_movk_i32 s16, 0x210
	s_ashr_i32 s6, s54, 3
	s_waitcnt lgkmcnt(0)
	v_mov_b32_e32 v158, v155
	v_mov_b32_e32 v159, v156
	v_mov_b32_e32 v155, v157
	v_pk_add_f32 v[154:155], v[158:159], v[154:155]
	v_readlane_b32 s10, v254, 18
	v_add_f32_e32 v1, v154, v155
	v_fmamk_f32 v1, v1, 0x3b800000, v213
	v_rsq_f32_e32 v1, v1
	v_readlane_b32 s11, v254, 19
	v_readlane_b32 s48, v254, 41
	v_readlane_b32 s49, v254, 42
	v_mul_f32_e32 v160, v0, v1
	v_add_u32_e32 v0, 0x20100, v3
	ds_read_b128 v[154:157], v0
	v_pk_mul_f32 v[128:129], v[128:129], v[160:161] op_sel_hi:[1,0]
	v_pk_mul_f32 v[120:121], v[120:121], v[160:161] op_sel_hi:[1,0]
	v_pk_mul_f32 v[124:125], v[124:125], v[160:161] op_sel_hi:[1,0]
	v_pk_mul_f32 v[126:127], v[126:127], v[160:161] op_sel_hi:[1,0]
	s_waitcnt lgkmcnt(0)
	v_mov_b32_e32 v0, v155
	v_mov_b32_e32 v1, v156
	v_mov_b32_e32 v155, v157
	v_pk_add_f32 v[0:1], v[0:1], v[154:155]
	v_pk_mul_f32 v[116:117], v[116:117], v[160:161] op_sel_hi:[1,0]
	v_add_f32_e32 v0, v0, v1
	v_fmamk_f32 v0, v0, 0x3b800000, v213
	v_rsq_f32_e32 v0, v0
	v_pk_mul_f32 v[118:119], v[118:119], v[160:161] op_sel_hi:[1,0]
	v_pk_mul_f32 v[130:131], v[130:131], v[160:161] op_sel_hi:[1,0]
	v_pk_mul_f32 v[122:123], v[122:123], v[160:161] op_sel_hi:[1,0]
	v_mul_f32_e32 v158, v148, v0
	v_add_u32_e32 v0, 0x20200, v3
	ds_read_b128 v[154:157], v0
	v_pk_mul_f32 v[112:113], v[112:113], v[158:159] op_sel_hi:[1,0]
	v_pk_mul_f32 v[100:101], v[100:101], v[158:159] op_sel_hi:[1,0]
	v_pk_mul_f32 v[108:109], v[108:109], v[158:159] op_sel_hi:[1,0]
	v_pk_mul_f32 v[110:111], v[110:111], v[158:159] op_sel_hi:[1,0]
	s_waitcnt lgkmcnt(0)
	v_mov_b32_e32 v0, v155
	v_mov_b32_e32 v1, v156
	v_mov_b32_e32 v155, v157
	v_pk_add_f32 v[0:1], v[0:1], v[154:155]
	v_pk_mul_f32 v[92:93], v[92:93], v[158:159] op_sel_hi:[1,0]
	v_add_f32_e32 v0, v0, v1
	v_fmamk_f32 v0, v0, 0x3b800000, v213
	v_rsq_f32_e32 v0, v0
	v_pk_mul_f32 v[94:95], v[94:95], v[158:159] op_sel_hi:[1,0]
	v_pk_mul_f32 v[102:103], v[102:103], v[158:159] op_sel_hi:[1,0]
	v_pk_mul_f32 v[114:115], v[114:115], v[158:159] op_sel_hi:[1,0]
	v_mul_f32_e32 v156, v150, v0
	v_add_u32_e32 v0, 0x20300, v3
	ds_read_b128 v[174:177], v0
	v_pk_mul_f32 v[84:85], v[84:85], v[156:157] op_sel_hi:[1,0]
	v_pk_mul_f32 v[96:97], v[96:97], v[156:157] op_sel_hi:[1,0]
	v_pk_mul_f32 v[98:99], v[98:99], v[156:157] op_sel_hi:[1,0]
	v_pk_mul_f32 v[76:77], v[76:77], v[156:157] op_sel_hi:[1,0]
	s_waitcnt lgkmcnt(0)
	v_mov_b32_e32 v0, v175
	v_mov_b32_e32 v1, v176
	v_mov_b32_e32 v175, v177
	v_pk_add_f32 v[0:1], v[0:1], v[174:175]
	v_pk_mul_f32 v[78:79], v[78:79], v[156:157] op_sel_hi:[1,0]
	v_add_f32_e32 v0, v0, v1
	v_fmamk_f32 v0, v0, 0x3b800000, v213
	v_rsq_f32_e32 v0, v0
	v_pk_mul_f32 v[86:87], v[86:87], v[156:157] op_sel_hi:[1,0]
	v_mul_f32_e32 v154, v152, v0
	v_add_u32_e32 v0, 0x20800, v3
	ds_read_b128 v[174:177], v0
	s_waitcnt vmcnt(0)
	v_pk_mul_f32 v[128:129], v[144:145], v[128:129]
	v_pk_mul_f32 v[112:113], v[144:145], v[112:113]
	v_pk_mul_f32 v[120:121], v[140:141], v[120:121]
	v_pk_mul_f32 v[100:101], v[140:141], v[100:101]
	s_waitcnt lgkmcnt(0)
	v_mov_b32_e32 v0, v175
	v_mov_b32_e32 v1, v176
	v_mov_b32_e32 v175, v177
	v_pk_add_f32 v[0:1], v[0:1], v[174:175]
	v_pk_mul_f32 v[84:85], v[140:141], v[84:85]
	v_add_f32_e32 v0, v0, v1
	v_fmamk_f32 v0, v0, 0x3b800000, v213
	v_rsq_f32_e32 v0, v0
	v_pk_mul_f32 v[72:73], v[72:73], v[154:155] op_sel_hi:[1,0]
	v_pk_mul_f32 v[80:81], v[80:81], v[154:155] op_sel_hi:[1,0]
	v_pk_mul_f32 v[82:83], v[82:83], v[154:155] op_sel_hi:[1,0]
	v_mul_f32_e32 v152, v162, v0
	v_add_u32_e32 v0, 0x20900, v3
	ds_read_b128 v[174:177], v0
	v_pk_mul_f32 v[72:73], v[140:141], v[72:73]
	v_pk_mul_f32 v[68:69], v[68:69], v[154:155] op_sel_hi:[1,0]
	v_pk_mul_f32 v[70:71], v[70:71], v[154:155] op_sel_hi:[1,0]
	v_pk_mul_f32 v[102:103], v[142:143], v[102:103]
	s_waitcnt lgkmcnt(0)
	v_mov_b32_e32 v0, v175
	v_mov_b32_e32 v1, v176
	v_mov_b32_e32 v175, v177
	v_pk_add_f32 v[0:1], v[0:1], v[174:175]
	v_pk_mul_f32 v[86:87], v[142:143], v[86:87]
	v_add_f32_e32 v0, v0, v1
	v_fmamk_f32 v0, v0, 0x3b800000, v213
	v_rsq_f32_e32 v0, v0
	v_pk_mul_f32 v[130:131], v[146:147], v[130:131]
	v_pk_mul_f32 v[74:75], v[74:75], v[154:155] op_sel_hi:[1,0]
	v_pk_mul_f32 v[122:123], v[142:143], v[122:123]
	v_mul_f32_e32 v150, v164, v0
	v_add_u32_e32 v0, 0x20a00, v3
	ds_read_b128 v[162:165], v0
	v_pk_mul_f32 v[56:57], v[56:57], v[150:151] op_sel_hi:[1,0]
	v_pk_mul_f32 v[20:21], v[20:21], v[150:151] op_sel_hi:[1,0]
	v_pk_mul_f32 v[22:23], v[22:23], v[150:151] op_sel_hi:[1,0]
	v_pk_mul_f32 v[56:57], v[136:137], v[56:57]
	s_waitcnt lgkmcnt(0)
	v_mov_b32_e32 v0, v163
	v_mov_b32_e32 v1, v164
	v_mov_b32_e32 v163, v165
	v_pk_add_f32 v[0:1], v[0:1], v[162:163]
	v_pk_mul_f32 v[22:23], v[142:143], v[22:23]
	v_add_f32_e32 v0, v0, v1
	v_fmamk_f32 v0, v0, 0x3b800000, v213
	v_rsq_f32_e32 v0, v0
	v_pk_mul_f32 v[20:21], v[140:141], v[20:21]
	v_pk_mul_f32 v[16:17], v[16:17], v[150:151] op_sel_hi:[1,0]
	v_pk_mul_f32 v[18:19], v[18:19], v[150:151] op_sel_hi:[1,0]
	v_mul_f32_e32 v148, v166, v0
	v_add_u32_e32 v0, 0x20b00, v3
	ds_read_b128 v[162:165], v0
	v_mov_b32_e32 v3, v217
	v_pk_mul_f32 v[48:49], v[48:49], v[148:149] op_sel_hi:[1,0]
	v_and_b32_e32 v153, 48, v3
	s_waitcnt lgkmcnt(0)
	v_mov_b32_e32 v0, v163
	v_mov_b32_e32 v1, v164
	v_mov_b32_e32 v163, v165
	v_pk_add_f32 v[0:1], v[0:1], v[162:163]
	v_pk_mul_f32 v[162:163], v[138:139], v[126:127]
	v_pk_mul_f32 v[126:127], v[136:137], v[124:125]
	v_cvt_pk_bf16_f32 v124, v128, v129
	v_pk_mul_f32 v[128:129], v[134:135], v[118:119]
	v_pk_mul_f32 v[118:119], v[132:133], v[116:117]
	v_cvt_pk_bf16_f32 v116, v120, v121
	v_pk_mul_f32 v[120:121], v[138:139], v[110:111]
	v_pk_mul_f32 v[110:111], v[136:137], v[108:109]
	v_cvt_pk_bf16_f32 v108, v112, v113
	v_pk_mul_f32 v[112:113], v[134:135], v[94:95]
	v_pk_mul_f32 v[94:95], v[132:133], v[92:93]
	v_cvt_pk_bf16_f32 v92, v100, v101
	v_pk_mul_f32 v[100:101], v[104:105], v[156:157] op_sel_hi:[1,0]
	v_add_f32_e32 v0, v0, v1
	v_pk_mul_f32 v[100:101], v[144:145], v[100:101]
	v_fmamk_f32 v0, v0, 0x3b800000, v213
	v_pk_mul_f32 v[104:105], v[138:139], v[98:99]
	v_pk_mul_f32 v[98:99], v[136:137], v[96:97]
	v_cvt_pk_bf16_f32 v96, v100, v101
	v_pk_mul_f32 v[100:101], v[134:135], v[78:79]
	v_pk_mul_f32 v[78:79], v[132:133], v[76:77]
	v_cvt_pk_bf16_f32 v76, v84, v85
	v_pk_mul_f32 v[84:85], v[88:89], v[154:155] op_sel_hi:[1,0]
	v_pk_mul_f32 v[64:65], v[64:65], v[152:153] op_sel_hi:[1,0]
	v_pk_mul_f32 v[12:13], v[12:13], v[152:153] op_sel_hi:[1,0]
	v_pk_mul_f32 v[14:15], v[14:15], v[152:153] op_sel_hi:[1,0]
	v_rsq_f32_e32 v0, v0
	v_pk_mul_f32 v[84:85], v[144:145], v[84:85]
	v_pk_mul_f32 v[64:65], v[144:145], v[64:65]
	v_pk_mul_f32 v[4:5], v[4:5], v[152:153] op_sel_hi:[1,0]
	v_pk_mul_f32 v[6:7], v[6:7], v[152:153] op_sel_hi:[1,0]
	v_pk_mul_f32 v[14:15], v[142:143], v[14:15]
	v_pk_mul_f32 v[12:13], v[140:141], v[12:13]
	v_pk_mul_f32 v[8:9], v[8:9], v[152:153] op_sel_hi:[1,0]
	v_pk_mul_f32 v[10:11], v[10:11], v[152:153] op_sel_hi:[1,0]
	v_pk_mul_f32 v[88:89], v[138:139], v[82:83]
	v_pk_mul_f32 v[82:83], v[136:137], v[80:81]
	v_cvt_pk_bf16_f32 v80, v84, v85
	v_pk_mul_f32 v[84:85], v[134:135], v[70:71]
	v_pk_mul_f32 v[70:71], v[132:133], v[68:69]
	v_cvt_pk_bf16_f32 v68, v72, v73
	v_pk_mul_f32 v[72:73], v[138:139], v[6:7]
	v_pk_mul_f32 v[6:7], v[136:137], v[4:5]
	v_cvt_pk_bf16_f32 v4, v64, v65
	v_pk_mul_f32 v[64:65], v[134:135], v[10:11]
	v_pk_mul_f32 v[10:11], v[132:133], v[8:9]
	v_cvt_pk_bf16_f32 v8, v12, v13
	v_cvt_pk_bf16_f32 v9, v14, v15
	v_pk_mul_f32 v[12:13], v[60:61], v[150:151] op_sel_hi:[1,0]
	v_pk_mul_f32 v[14:15], v[62:63], v[150:151] op_sel_hi:[1,0]
	v_pk_mul_f32 v[12:13], v[144:145], v[12:13]
	v_pk_mul_f32 v[14:15], v[146:147], v[14:15]
	v_cvt_pk_bf16_f32 v12, v12, v13
	v_cvt_pk_bf16_f32 v13, v14, v15
	v_cvt_pk_bf16_f32 v14, v56, v57
	v_pk_mul_f32 v[56:57], v[134:135], v[18:19]
	v_pk_mul_f32 v[18:19], v[132:133], v[16:17]
	v_cvt_pk_bf16_f32 v16, v20, v21
	v_cvt_pk_bf16_f32 v17, v22, v23
	v_pk_mul_f32 v[20:21], v[52:53], v[148:149] op_sel_hi:[1,0]
	v_pk_mul_f32 v[22:23], v[54:55], v[148:149] op_sel_hi:[1,0]
	v_pk_mul_f32 v[28:29], v[28:29], v[148:149] op_sel_hi:[1,0]
	v_pk_mul_f32 v[30:31], v[30:31], v[148:149] op_sel_hi:[1,0]
	v_mul_f32_e32 v0, v168, v0
	v_pk_mul_f32 v[22:23], v[146:147], v[22:23]
	v_pk_mul_f32 v[20:21], v[144:145], v[20:21]
	v_pk_mul_f32 v[48:49], v[136:137], v[48:49]
	v_pk_mul_f32 v[30:31], v[142:143], v[30:31]
	v_pk_mul_f32 v[28:29], v[140:141], v[28:29]
	v_pk_mul_f32 v[24:25], v[24:25], v[148:149] op_sel_hi:[1,0]
	v_pk_mul_f32 v[26:27], v[26:27], v[148:149] op_sel_hi:[1,0]
	v_cvt_pk_bf16_f32 v20, v20, v21
	v_cvt_pk_bf16_f32 v21, v22, v23
	v_cvt_pk_bf16_f32 v22, v48, v49
	v_pk_mul_f32 v[48:49], v[134:135], v[26:27]
	v_pk_mul_f32 v[26:27], v[132:133], v[24:25]
	v_cvt_pk_bf16_f32 v24, v28, v29
	v_cvt_pk_bf16_f32 v25, v30, v31
	v_pk_mul_f32 v[28:29], v[44:45], v[0:1] op_sel_hi:[1,0]
	v_pk_mul_f32 v[30:31], v[46:47], v[0:1] op_sel_hi:[1,0]
	v_pk_mul_f32 v[40:41], v[40:41], v[0:1] op_sel_hi:[1,0]
	v_pk_mul_f32 v[42:43], v[42:43], v[0:1] op_sel_hi:[1,0]
	v_pk_mul_f32 v[36:37], v[36:37], v[0:1] op_sel_hi:[1,0]
	v_pk_mul_f32 v[38:39], v[38:39], v[0:1] op_sel_hi:[1,0]
	v_pk_mul_f32 v[32:33], v[32:33], v[0:1] op_sel_hi:[1,0]
	v_pk_mul_f32 v[0:1], v[34:35], v[0:1] op_sel_hi:[1,0]
	v_readfirstlane_b32 s7, v3
	v_pk_mul_f32 v[0:1], v[134:135], v[0:1]
	v_pk_mul_f32 v[34:35], v[132:133], v[32:33]
	s_ashr_i32 s8, s7, 2
	v_pk_mul_f32 v[36:37], v[140:141], v[36:37]
	v_cvt_pk_bf16_f32 v34, v34, v35
	v_cvt_pk_bf16_f32 v35, v0, v1
	v_bfi_b32 v1, -16, s8, v3
	v_cvt_pk_bf16_f32 v32, v36, v37
	v_mul_lo_u32 v36, v1, s16
	v_add3_u32 v175, 0, v36, v153
	v_ashrrev_i32_e32 v36, 3, v3
	v_pk_mul_f32 v[30:31], v[146:147], v[30:31]
	v_pk_mul_f32 v[28:29], v[144:145], v[28:29]
	v_pk_mul_f32 v[40:41], v[136:137], v[40:41]
	v_pk_mul_f32 v[38:39], v[142:143], v[38:39]
	v_ashrrev_i32_e32 v37, 31, v36
	v_cvt_pk_bf16_f32 v28, v28, v29
	v_cvt_pk_bf16_f32 v29, v30, v31
	v_cvt_pk_bf16_f32 v30, v40, v41
	v_cvt_pk_bf16_f32 v33, v38, v39
	v_and_b32_e32 v38, 15, v3
	v_bfe_u32 v39, v3, 4, 2
	v_lshlrev_b64 v[44:45], 13, v[36:37]
	v_lshlrev_b32_e32 v37, 3, v3
	v_lshlrev_b32_e32 v40, 4, v3
	v_bfe_u32 v3, v3, 2, 2
	v_mul_lo_u32 v36, v36, s16
	v_and_b32_e32 v180, 0x70, v40
	v_lshl_or_b32 v3, v39, 2, v3
	s_ashr_i32 s7, s6, 31
	s_lshl_b32 s8, s53, 8
	v_add3_u32 v170, s10, v36, v180
	v_mul_u32_u24_e32 v38, 0x210, v38
	v_add3_u32 v168, s11, v36, v180
	v_mul_u32_u24_e32 v3, 0x210, v3
	v_and_b32_e32 v36, 24, v37
	s_lshl_b64 s[12:13], s[6:7], 21
	s_ashr_i32 s9, s8, 31
	v_add3_u32 v174, s10, v153, v38
	v_add3_u32 v173, s11, v153, v38
	v_add3_u32 v169, s10, v3, v36
	v_add3_u32 v3, s11, v3, v36
	s_lshl_b64 s[10:11], s[6:7], 22
	s_add_u32 s12, s60, s12
	s_addc_u32 s13, s61, s13
	v_lshl_add_u64 v[44:45], s[12:13], 0, v[44:45]
	s_lshl_b32 s12, s0, 11
	s_ashr_i32 s13, s12, 31
	v_cvt_pk_bf16_f32 v93, v102, v103
	v_pk_mul_f32 v[102:103], v[106:107], v[156:157] op_sel_hi:[1,0]
	v_cvt_pk_bf16_f32 v77, v86, v87
	v_pk_mul_f32 v[86:87], v[90:91], v[154:155] op_sel_hi:[1,0]
	v_mul_lo_u32 v36, v149, s16
	v_lshl_add_u64 v[44:45], s[12:13], 1, v[44:45]
	s_lshl_b64 s[8:9], s[8:9], 1
	v_cvt_pk_bf16_f32 v125, v130, v131
	v_cvt_pk_bf16_f32 v126, v126, v127
	v_cvt_pk_bf16_f32 v127, v162, v163
	v_pk_mul_f32 v[114:115], v[146:147], v[114:115]
	v_pk_mul_f32 v[102:103], v[146:147], v[102:103]
	v_pk_mul_f32 v[86:87], v[146:147], v[86:87]
	v_pk_mul_f32 v[74:75], v[142:143], v[74:75]
	v_add3_u32 v176, s15, v151, v36
	v_lshl_add_u64 v[44:45], v[44:45], 0, s[8:9]
	v_cvt_pk_bf16_f32 v117, v122, v123
	v_cvt_pk_bf16_f32 v118, v118, v119
	v_cvt_pk_bf16_f32 v119, v128, v129
	v_cvt_pk_bf16_f32 v109, v114, v115
	v_cvt_pk_bf16_f32 v110, v110, v111
	v_cvt_pk_bf16_f32 v111, v120, v121
	v_cvt_pk_bf16_f32 v94, v94, v95
	v_cvt_pk_bf16_f32 v95, v112, v113
	v_cvt_pk_bf16_f32 v97, v102, v103
	v_cvt_pk_bf16_f32 v98, v98, v99
	v_cvt_pk_bf16_f32 v99, v104, v105
	v_cvt_pk_bf16_f32 v78, v78, v79
	v_cvt_pk_bf16_f32 v79, v100, v101
	v_cvt_pk_bf16_f32 v81, v86, v87
	v_cvt_pk_bf16_f32 v82, v82, v83
	v_cvt_pk_bf16_f32 v83, v88, v89
	v_cvt_pk_bf16_f32 v69, v74, v75
	v_cvt_pk_bf16_f32 v70, v70, v71
	v_cvt_pk_bf16_f32 v71, v84, v85
	s_waitcnt lgkmcnt(0)
	v_pk_mul_f32 v[66:67], v[66:67], v[152:153] op_sel_hi:[1,0]
	v_pk_mul_f32 v[58:59], v[58:59], v[150:151] op_sel_hi:[1,0]
	v_pk_mul_f32 v[50:51], v[50:51], v[148:149] op_sel_hi:[1,0]
	v_pk_mul_f32 v[42:43], v[138:139], v[42:43]
	v_pk_mul_f32 v[66:67], v[146:147], v[66:67]
	v_pk_mul_f32 v[58:59], v[138:139], v[58:59]
	v_pk_mul_f32 v[50:51], v[138:139], v[50:51]
	v_cvt_pk_bf16_f32 v31, v42, v43
	v_cvt_pk_bf16_f32 v5, v66, v67
	v_cvt_pk_bf16_f32 v6, v6, v7
	v_cvt_pk_bf16_f32 v7, v72, v73
	v_cvt_pk_bf16_f32 v10, v10, v11
	v_cvt_pk_bf16_f32 v11, v64, v65
	v_cvt_pk_bf16_f32 v15, v58, v59
	v_cvt_pk_bf16_f32 v18, v18, v19
	v_cvt_pk_bf16_f32 v19, v56, v57
	v_cvt_pk_bf16_f32 v23, v50, v51
	v_cvt_pk_bf16_f32 v26, v26, v27
	v_cvt_pk_bf16_f32 v27, v48, v49
	v_lshl_add_u64 v[210:211], v[44:45], 0, v[180:181]
	v_mov_b32_e32 v187, v170
	v_mov_b32_e32 v249, v174
	v_mov_b32_e32 v189, v171
	v_mov_b32_e32 v222, v172
	v_add_u32_e32 v218, 0x10800, v176
	v_add_u32_e32 v219, 0x10800, v175
	v_mov_b32_e32 v180, v169
	global_load_dwordx4 v[236:239], v[210:211], off
	global_load_dwordx4 v[240:243], v[210:211], off offset:128
	global_load_dwordx4 v[164:167], v[210:211], off offset:256
	global_load_dwordx4 v[182:185], v[210:211], off offset:384
	s_barrier
	ds_write_b128 v176, v[124:127]
	ds_write_b128 v176, v[116:119] offset:256
	ds_write_b128 v176, v[108:111] offset:8448
	ds_write_b128 v176, v[92:95] offset:8704
	ds_write_b128 v176, v[96:99] offset:16896
	ds_write_b128 v176, v[76:79] offset:17152
	ds_write_b128 v176, v[80:83] offset:25344
	ds_write_b128 v176, v[68:71] offset:25600
	ds_write_b128 v218, v[4:7]
	ds_write_b128 v218, v[8:11] offset:256
	ds_write_b128 v218, v[12:15] offset:8448
	ds_write_b128 v218, v[16:19] offset:8704
	ds_write_b128 v218, v[20:23] offset:16896
	ds_write_b128 v218, v[24:27] offset:17152
	ds_write_b128 v218, v[28:31] offset:25344
	ds_write_b128 v218, v[32:35] offset:25600
	s_waitcnt lgkmcnt(0)
	s_barrier
	ds_read_b128 v[132:135], v175
	ds_read_b128 v[136:139], v175 offset:64
	ds_read_b128 v[140:143], v175 offset:128
	ds_read_b128 v[144:147], v175 offset:192
	ds_read_b128 v[148:151], v175 offset:256
	ds_read_b128 v[152:155], v175 offset:320
	ds_read_b128 v[156:159], v175 offset:384
	ds_read_b128 v[160:163], v175 offset:448
	ds_read_b128 v[190:193], v219
	ds_read_b128 v[194:197], v219 offset:64
	ds_read_b128 v[198:201], v219 offset:128
	ds_read_b128 v[202:205], v219 offset:192
	ds_read_b128 v[206:209], v219 offset:256
	ds_read_b128 v[224:227], v219 offset:320
	ds_read_b128 v[228:231], v219 offset:384
	ds_read_b128 v[232:235], v219 offset:448
	s_waitcnt lgkmcnt(0)
	s_barrier
	s_waitcnt vmcnt(0)
	ds_write_b128 v187, v[236:239]
	ds_write_b128 v187, v[240:243] offset:128
	ds_write_b128 v187, v[164:167] offset:256
	ds_write_b128 v187, v[182:185] offset:384
	v_add_co_u32_e32 v218, vcc, 0x80000, v210
	s_nop 1
	v_addc_co_u32_e32 v219, vcc, 0, v211, vcc
	global_load_dwordx4 v[236:239], v[218:219], off
	global_load_dwordx4 v[240:243], v[218:219], off offset:128
	global_load_dwordx4 v[164:167], v[218:219], off offset:256
	global_load_dwordx4 v[182:185], v[218:219], off offset:384
	s_waitcnt lgkmcnt(0)
	s_barrier
	ds_read_b128 v[0:3], v249
	ds_read_b128 v[168:171], v249 offset:64
	ds_read_b128 v[172:175], v249 offset:128
	ds_read_b128 v[176:179], v249 offset:192
	s_waitcnt lgkmcnt(3)
	v_mfma_f32_16x16x32_bf16 v[4:7], v[0:3], v[132:135], 0
	v_mfma_f32_16x16x32_bf16 v[68:71], v[0:3], v[190:193], 0
	ds_read_b128 v[0:3], v249 offset:256
	s_waitcnt lgkmcnt(3)
	v_mfma_f32_16x16x32_bf16 v[4:7], v[168:171], v[136:139], v[4:7]
	v_mfma_f32_16x16x32_bf16 v[68:71], v[168:171], v[194:197], v[68:71]
	ds_read_b128 v[168:171], v249 offset:320
	s_waitcnt lgkmcnt(3)
	v_mfma_f32_16x16x32_bf16 v[4:7], v[172:175], v[140:143], v[4:7]
	v_mfma_f32_16x16x32_bf16 v[68:71], v[172:175], v[198:201], v[68:71]
	ds_read_b128 v[172:175], v249 offset:384
	s_waitcnt lgkmcnt(3)
	v_mfma_f32_16x16x32_bf16 v[4:7], v[176:179], v[144:147], v[4:7]
	v_mfma_f32_16x16x32_bf16 v[68:71], v[176:179], v[202:205], v[68:71]
	ds_read_b128 v[176:179], v249 offset:448
	s_waitcnt lgkmcnt(3)
	v_mfma_f32_16x16x32_bf16 v[4:7], v[0:3], v[148:151], v[4:7]
	v_mfma_f32_16x16x32_bf16 v[68:71], v[0:3], v[206:209], v[68:71]
	ds_read_b128 v[0:3], v249 offset:8448
	s_waitcnt lgkmcnt(3)
	v_mfma_f32_16x16x32_bf16 v[4:7], v[168:171], v[152:155], v[4:7]
	v_mfma_f32_16x16x32_bf16 v[68:71], v[168:171], v[224:227], v[68:71]
	ds_read_b128 v[168:171], v249 offset:8512
	s_waitcnt lgkmcnt(3)
	v_mfma_f32_16x16x32_bf16 v[4:7], v[172:175], v[156:159], v[4:7]
	v_mfma_f32_16x16x32_bf16 v[68:71], v[172:175], v[228:231], v[68:71]
	ds_read_b128 v[172:175], v249 offset:8576
	s_waitcnt lgkmcnt(3)
	v_mfma_f32_16x16x32_bf16 v[4:7], v[176:179], v[160:163], v[4:7]
	v_mfma_f32_16x16x32_bf16 v[68:71], v[176:179], v[232:235], v[68:71]
	ds_read_b128 v[176:179], v249 offset:8640
	s_waitcnt lgkmcnt(3)
	v_mfma_f32_16x16x32_bf16 v[8:11], v[0:3], v[132:135], 0
	v_mfma_f32_16x16x32_bf16 v[72:75], v[0:3], v[190:193], 0
	ds_read_b128 v[0:3], v249 offset:8704
	s_waitcnt lgkmcnt(3)
	v_mfma_f32_16x16x32_bf16 v[8:11], v[168:171], v[136:139], v[8:11]
	v_mfma_f32_16x16x32_bf16 v[72:75], v[168:171], v[194:197], v[72:75]
	ds_read_b128 v[168:171], v249 offset:8768
	s_waitcnt lgkmcnt(3)
	v_mfma_f32_16x16x32_bf16 v[8:11], v[172:175], v[140:143], v[8:11]
	v_mfma_f32_16x16x32_bf16 v[72:75], v[172:175], v[198:201], v[72:75]
	ds_read_b128 v[172:175], v249 offset:8832
	s_waitcnt lgkmcnt(3)
	v_mfma_f32_16x16x32_bf16 v[8:11], v[176:179], v[144:147], v[8:11]
	v_mfma_f32_16x16x32_bf16 v[72:75], v[176:179], v[202:205], v[72:75]
	ds_read_b128 v[176:179], v249 offset:8896
	s_waitcnt lgkmcnt(3)
	v_mfma_f32_16x16x32_bf16 v[8:11], v[0:3], v[148:151], v[8:11]
	v_mfma_f32_16x16x32_bf16 v[72:75], v[0:3], v[206:209], v[72:75]
	ds_read_b128 v[0:3], v249 offset:16896
	s_waitcnt lgkmcnt(3)
	v_mfma_f32_16x16x32_bf16 v[8:11], v[168:171], v[152:155], v[8:11]
	v_mfma_f32_16x16x32_bf16 v[72:75], v[168:171], v[224:227], v[72:75]
	ds_read_b128 v[168:171], v249 offset:16960
	s_waitcnt lgkmcnt(3)
	v_mfma_f32_16x16x32_bf16 v[8:11], v[172:175], v[156:159], v[8:11]
	v_mfma_f32_16x16x32_bf16 v[72:75], v[172:175], v[228:231], v[72:75]
	ds_read_b128 v[172:175], v249 offset:17024
	s_waitcnt lgkmcnt(3)
	v_mfma_f32_16x16x32_bf16 v[8:11], v[176:179], v[160:163], v[8:11]
	v_mfma_f32_16x16x32_bf16 v[72:75], v[176:179], v[232:235], v[72:75]
	ds_read_b128 v[176:179], v249 offset:17088
	s_waitcnt lgkmcnt(3)
	v_mfma_f32_16x16x32_bf16 v[12:15], v[0:3], v[132:135], 0
	v_mfma_f32_16x16x32_bf16 v[76:79], v[0:3], v[190:193], 0
	ds_read_b128 v[0:3], v249 offset:17152
	s_waitcnt lgkmcnt(3)
	v_mfma_f32_16x16x32_bf16 v[12:15], v[168:171], v[136:139], v[12:15]
	v_mfma_f32_16x16x32_bf16 v[76:79], v[168:171], v[194:197], v[76:79]
	ds_read_b128 v[168:171], v249 offset:17216
	s_waitcnt lgkmcnt(3)
	v_mfma_f32_16x16x32_bf16 v[12:15], v[172:175], v[140:143], v[12:15]
	v_mfma_f32_16x16x32_bf16 v[76:79], v[172:175], v[198:201], v[76:79]
	ds_read_b128 v[172:175], v249 offset:17280
	s_waitcnt lgkmcnt(3)
	v_mfma_f32_16x16x32_bf16 v[12:15], v[176:179], v[144:147], v[12:15]
	v_mfma_f32_16x16x32_bf16 v[76:79], v[176:179], v[202:205], v[76:79]
	ds_read_b128 v[176:179], v249 offset:17344
	s_waitcnt lgkmcnt(3)
	v_mfma_f32_16x16x32_bf16 v[12:15], v[0:3], v[148:151], v[12:15]
	v_mfma_f32_16x16x32_bf16 v[76:79], v[0:3], v[206:209], v[76:79]
	ds_read_b128 v[0:3], v249 offset:25344
	s_waitcnt lgkmcnt(3)
	v_mfma_f32_16x16x32_bf16 v[12:15], v[168:171], v[152:155], v[12:15]
	v_mfma_f32_16x16x32_bf16 v[76:79], v[168:171], v[224:227], v[76:79]
	ds_read_b128 v[168:171], v249 offset:25408
	s_waitcnt lgkmcnt(3)
	v_mfma_f32_16x16x32_bf16 v[12:15], v[172:175], v[156:159], v[12:15]
	v_mfma_f32_16x16x32_bf16 v[76:79], v[172:175], v[228:231], v[76:79]
	ds_read_b128 v[172:175], v249 offset:25472
	s_waitcnt lgkmcnt(3)
	v_mfma_f32_16x16x32_bf16 v[12:15], v[176:179], v[160:163], v[12:15]
	v_mfma_f32_16x16x32_bf16 v[76:79], v[176:179], v[232:235], v[76:79]
	ds_read_b128 v[176:179], v249 offset:25536
	s_waitcnt lgkmcnt(3)
	v_mfma_f32_16x16x32_bf16 v[16:19], v[0:3], v[132:135], 0
	v_mfma_f32_16x16x32_bf16 v[80:83], v[0:3], v[190:193], 0
	ds_read_b128 v[0:3], v249 offset:25600
	s_waitcnt lgkmcnt(3)
	v_mfma_f32_16x16x32_bf16 v[16:19], v[168:171], v[136:139], v[16:19]
	v_mfma_f32_16x16x32_bf16 v[80:83], v[168:171], v[194:197], v[80:83]
	ds_read_b128 v[168:171], v249 offset:25664
	s_waitcnt lgkmcnt(3)
	v_mfma_f32_16x16x32_bf16 v[16:19], v[172:175], v[140:143], v[16:19]
	v_mfma_f32_16x16x32_bf16 v[80:83], v[172:175], v[198:201], v[80:83]
	ds_read_b128 v[172:175], v249 offset:25728
	s_waitcnt lgkmcnt(3)
	v_mfma_f32_16x16x32_bf16 v[16:19], v[176:179], v[144:147], v[16:19]
	v_mfma_f32_16x16x32_bf16 v[80:83], v[176:179], v[202:205], v[80:83]
	ds_read_b128 v[176:179], v249 offset:25792
	s_waitcnt lgkmcnt(3)
	v_mfma_f32_16x16x32_bf16 v[16:19], v[0:3], v[148:151], v[16:19]
	v_mfma_f32_16x16x32_bf16 v[80:83], v[0:3], v[206:209], v[80:83]
	s_waitcnt lgkmcnt(2)
	v_mfma_f32_16x16x32_bf16 v[16:19], v[168:171], v[152:155], v[16:19]
	v_mfma_f32_16x16x32_bf16 v[80:83], v[168:171], v[224:227], v[80:83]
	s_waitcnt lgkmcnt(1)
	v_mfma_f32_16x16x32_bf16 v[16:19], v[172:175], v[156:159], v[16:19]
	v_mfma_f32_16x16x32_bf16 v[80:83], v[172:175], v[228:231], v[80:83]
	s_waitcnt lgkmcnt(0)
	v_mfma_f32_16x16x32_bf16 v[16:19], v[176:179], v[160:163], v[16:19]
	v_mfma_f32_16x16x32_bf16 v[80:83], v[176:179], v[232:235], v[80:83]
	s_waitcnt vmcnt(0)
	ds_write_b128 v187, v[236:239] offset:33792
	ds_write_b128 v187, v[240:243] offset:33920
	ds_write_b128 v187, v[164:167] offset:34048
	ds_write_b128 v187, v[182:185] offset:34176
	v_add_co_u32_e32 v218, vcc, 0x100000, v210
	s_nop 1
	v_addc_co_u32_e32 v219, vcc, 0, v211, vcc
	global_load_dwordx4 v[236:239], v[218:219], off
	global_load_dwordx4 v[240:243], v[218:219], off offset:128
	global_load_dwordx4 v[164:167], v[218:219], off offset:256
	global_load_dwordx4 v[182:185], v[218:219], off offset:384
	s_waitcnt lgkmcnt(0)
	s_barrier
	ds_read_b128 v[0:3], v249 offset:33792
	ds_read_b128 v[168:171], v249 offset:33856
	ds_read_b128 v[172:175], v249 offset:33920
	ds_read_b128 v[176:179], v249 offset:33984
	s_waitcnt lgkmcnt(3)
	v_mfma_f32_16x16x32_bf16 v[20:23], v[0:3], v[132:135], 0
	v_mfma_f32_16x16x32_bf16 v[84:87], v[0:3], v[190:193], 0
	ds_read_b128 v[0:3], v249 offset:34048
	s_waitcnt lgkmcnt(3)
	v_mfma_f32_16x16x32_bf16 v[20:23], v[168:171], v[136:139], v[20:23]
	v_mfma_f32_16x16x32_bf16 v[84:87], v[168:171], v[194:197], v[84:87]
	ds_read_b128 v[168:171], v249 offset:34112
	s_waitcnt lgkmcnt(3)
	v_mfma_f32_16x16x32_bf16 v[20:23], v[172:175], v[140:143], v[20:23]
	v_mfma_f32_16x16x32_bf16 v[84:87], v[172:175], v[198:201], v[84:87]
	ds_read_b128 v[172:175], v249 offset:34176
	s_waitcnt lgkmcnt(3)
	v_mfma_f32_16x16x32_bf16 v[20:23], v[176:179], v[144:147], v[20:23]
	v_mfma_f32_16x16x32_bf16 v[84:87], v[176:179], v[202:205], v[84:87]
	ds_read_b128 v[176:179], v249 offset:34240
	s_waitcnt lgkmcnt(3)
	v_mfma_f32_16x16x32_bf16 v[20:23], v[0:3], v[148:151], v[20:23]
	v_mfma_f32_16x16x32_bf16 v[84:87], v[0:3], v[206:209], v[84:87]
	ds_read_b128 v[0:3], v249 offset:42240
	s_waitcnt lgkmcnt(3)
	v_mfma_f32_16x16x32_bf16 v[20:23], v[168:171], v[152:155], v[20:23]
	v_mfma_f32_16x16x32_bf16 v[84:87], v[168:171], v[224:227], v[84:87]
	ds_read_b128 v[168:171], v249 offset:42304
	s_waitcnt lgkmcnt(3)
	v_mfma_f32_16x16x32_bf16 v[20:23], v[172:175], v[156:159], v[20:23]
	v_mfma_f32_16x16x32_bf16 v[84:87], v[172:175], v[228:231], v[84:87]
	ds_read_b128 v[172:175], v249 offset:42368
	s_waitcnt lgkmcnt(3)
	v_mfma_f32_16x16x32_bf16 v[20:23], v[176:179], v[160:163], v[20:23]
	v_mfma_f32_16x16x32_bf16 v[84:87], v[176:179], v[232:235], v[84:87]
	ds_read_b128 v[176:179], v249 offset:42432
	s_waitcnt lgkmcnt(3)
	v_mfma_f32_16x16x32_bf16 v[24:27], v[0:3], v[132:135], 0
	v_mfma_f32_16x16x32_bf16 v[88:91], v[0:3], v[190:193], 0
	ds_read_b128 v[0:3], v249 offset:42496
	s_waitcnt lgkmcnt(3)
	v_mfma_f32_16x16x32_bf16 v[24:27], v[168:171], v[136:139], v[24:27]
	v_mfma_f32_16x16x32_bf16 v[88:91], v[168:171], v[194:197], v[88:91]
	ds_read_b128 v[168:171], v249 offset:42560
	s_waitcnt lgkmcnt(3)
	v_mfma_f32_16x16x32_bf16 v[24:27], v[172:175], v[140:143], v[24:27]
	v_mfma_f32_16x16x32_bf16 v[88:91], v[172:175], v[198:201], v[88:91]
	ds_read_b128 v[172:175], v249 offset:42624
	s_waitcnt lgkmcnt(3)
	v_mfma_f32_16x16x32_bf16 v[24:27], v[176:179], v[144:147], v[24:27]
	v_mfma_f32_16x16x32_bf16 v[88:91], v[176:179], v[202:205], v[88:91]
	ds_read_b128 v[176:179], v249 offset:42688
	s_waitcnt lgkmcnt(3)
	v_mfma_f32_16x16x32_bf16 v[24:27], v[0:3], v[148:151], v[24:27]
	v_mfma_f32_16x16x32_bf16 v[88:91], v[0:3], v[206:209], v[88:91]
	ds_read_b128 v[0:3], v249 offset:50688
	s_waitcnt lgkmcnt(3)
	v_mfma_f32_16x16x32_bf16 v[24:27], v[168:171], v[152:155], v[24:27]
	v_mfma_f32_16x16x32_bf16 v[88:91], v[168:171], v[224:227], v[88:91]
	ds_read_b128 v[168:171], v249 offset:50752
	s_waitcnt lgkmcnt(3)
	v_mfma_f32_16x16x32_bf16 v[24:27], v[172:175], v[156:159], v[24:27]
	v_mfma_f32_16x16x32_bf16 v[88:91], v[172:175], v[228:231], v[88:91]
	ds_read_b128 v[172:175], v249 offset:50816
	s_waitcnt lgkmcnt(3)
	v_mfma_f32_16x16x32_bf16 v[24:27], v[176:179], v[160:163], v[24:27]
	v_mfma_f32_16x16x32_bf16 v[88:91], v[176:179], v[232:235], v[88:91]
	ds_read_b128 v[176:179], v249 offset:50880
	s_waitcnt lgkmcnt(3)
	v_mfma_f32_16x16x32_bf16 v[28:31], v[0:3], v[132:135], 0
	v_mfma_f32_16x16x32_bf16 v[92:95], v[0:3], v[190:193], 0
	ds_read_b128 v[0:3], v249 offset:50944
	s_waitcnt lgkmcnt(3)
	v_mfma_f32_16x16x32_bf16 v[28:31], v[168:171], v[136:139], v[28:31]
	v_mfma_f32_16x16x32_bf16 v[92:95], v[168:171], v[194:197], v[92:95]
	ds_read_b128 v[168:171], v249 offset:51008
	s_waitcnt lgkmcnt(3)
	v_mfma_f32_16x16x32_bf16 v[28:31], v[172:175], v[140:143], v[28:31]
	v_mfma_f32_16x16x32_bf16 v[92:95], v[172:175], v[198:201], v[92:95]
	ds_read_b128 v[172:175], v249 offset:51072
	s_waitcnt lgkmcnt(3)
	v_mfma_f32_16x16x32_bf16 v[28:31], v[176:179], v[144:147], v[28:31]
	v_mfma_f32_16x16x32_bf16 v[92:95], v[176:179], v[202:205], v[92:95]
	ds_read_b128 v[176:179], v249 offset:51136
	s_waitcnt lgkmcnt(3)
	v_mfma_f32_16x16x32_bf16 v[28:31], v[0:3], v[148:151], v[28:31]
	v_mfma_f32_16x16x32_bf16 v[92:95], v[0:3], v[206:209], v[92:95]
	ds_read_b128 v[0:3], v249 offset:59136
	s_waitcnt lgkmcnt(3)
	v_mfma_f32_16x16x32_bf16 v[28:31], v[168:171], v[152:155], v[28:31]
	v_mfma_f32_16x16x32_bf16 v[92:95], v[168:171], v[224:227], v[92:95]
	ds_read_b128 v[168:171], v249 offset:59200
	s_waitcnt lgkmcnt(3)
	v_mfma_f32_16x16x32_bf16 v[28:31], v[172:175], v[156:159], v[28:31]
	v_mfma_f32_16x16x32_bf16 v[92:95], v[172:175], v[228:231], v[92:95]
	ds_read_b128 v[172:175], v249 offset:59264
	s_waitcnt lgkmcnt(3)
	v_mfma_f32_16x16x32_bf16 v[28:31], v[176:179], v[160:163], v[28:31]
	v_mfma_f32_16x16x32_bf16 v[92:95], v[176:179], v[232:235], v[92:95]
	ds_read_b128 v[176:179], v249 offset:59328
	s_waitcnt lgkmcnt(3)
	v_mfma_f32_16x16x32_bf16 v[32:35], v[0:3], v[132:135], 0
	v_mfma_f32_16x16x32_bf16 v[96:99], v[0:3], v[190:193], 0
	ds_read_b128 v[0:3], v249 offset:59392
	s_waitcnt lgkmcnt(3)
	v_mfma_f32_16x16x32_bf16 v[32:35], v[168:171], v[136:139], v[32:35]
	v_mfma_f32_16x16x32_bf16 v[96:99], v[168:171], v[194:197], v[96:99]
	ds_read_b128 v[168:171], v249 offset:59456
	s_waitcnt lgkmcnt(3)
	v_mfma_f32_16x16x32_bf16 v[32:35], v[172:175], v[140:143], v[32:35]
	v_mfma_f32_16x16x32_bf16 v[96:99], v[172:175], v[198:201], v[96:99]
	ds_read_b128 v[172:175], v249 offset:59520
	s_waitcnt lgkmcnt(3)
	v_mfma_f32_16x16x32_bf16 v[32:35], v[176:179], v[144:147], v[32:35]
	v_mfma_f32_16x16x32_bf16 v[96:99], v[176:179], v[202:205], v[96:99]
	ds_read_b128 v[176:179], v249 offset:59584
	s_waitcnt lgkmcnt(3)
	v_mfma_f32_16x16x32_bf16 v[32:35], v[0:3], v[148:151], v[32:35]
	v_mfma_f32_16x16x32_bf16 v[96:99], v[0:3], v[206:209], v[96:99]
	s_waitcnt lgkmcnt(2)
	v_mfma_f32_16x16x32_bf16 v[32:35], v[168:171], v[152:155], v[32:35]
	v_mfma_f32_16x16x32_bf16 v[96:99], v[168:171], v[224:227], v[96:99]
	s_waitcnt lgkmcnt(1)
	v_mfma_f32_16x16x32_bf16 v[32:35], v[172:175], v[156:159], v[32:35]
	v_mfma_f32_16x16x32_bf16 v[96:99], v[172:175], v[228:231], v[96:99]
	s_waitcnt lgkmcnt(0)
	v_mfma_f32_16x16x32_bf16 v[32:35], v[176:179], v[160:163], v[32:35]
	v_mfma_f32_16x16x32_bf16 v[96:99], v[176:179], v[232:235], v[96:99]
	s_waitcnt vmcnt(0)
	ds_write_b128 v187, v[236:239]
	ds_write_b128 v187, v[240:243] offset:128
	ds_write_b128 v187, v[164:167] offset:256
	ds_write_b128 v187, v[182:185] offset:384
	v_add_co_u32_e32 v218, vcc, 0x180000, v210
	s_nop 1
	v_addc_co_u32_e32 v219, vcc, 0, v211, vcc
	global_load_dwordx4 v[236:239], v[218:219], off
	global_load_dwordx4 v[240:243], v[218:219], off offset:128
	global_load_dwordx4 v[164:167], v[218:219], off offset:256
	global_load_dwordx4 v[182:185], v[218:219], off offset:384
	s_waitcnt lgkmcnt(0)
	s_barrier
	ds_read_b128 v[0:3], v249
	ds_read_b128 v[168:171], v249 offset:64
	ds_read_b128 v[172:175], v249 offset:128
	ds_read_b128 v[176:179], v249 offset:192
	s_waitcnt lgkmcnt(3)
	v_mfma_f32_16x16x32_bf16 v[36:39], v[0:3], v[132:135], 0
	v_mfma_f32_16x16x32_bf16 v[100:103], v[0:3], v[190:193], 0
	ds_read_b128 v[0:3], v249 offset:256
	s_waitcnt lgkmcnt(3)
	v_mfma_f32_16x16x32_bf16 v[36:39], v[168:171], v[136:139], v[36:39]
	v_mfma_f32_16x16x32_bf16 v[100:103], v[168:171], v[194:197], v[100:103]
	ds_read_b128 v[168:171], v249 offset:320
	s_waitcnt lgkmcnt(3)
	v_mfma_f32_16x16x32_bf16 v[36:39], v[172:175], v[140:143], v[36:39]
	v_mfma_f32_16x16x32_bf16 v[100:103], v[172:175], v[198:201], v[100:103]
	ds_read_b128 v[172:175], v249 offset:384
	s_waitcnt lgkmcnt(3)
	v_mfma_f32_16x16x32_bf16 v[36:39], v[176:179], v[144:147], v[36:39]
	v_mfma_f32_16x16x32_bf16 v[100:103], v[176:179], v[202:205], v[100:103]
	ds_read_b128 v[176:179], v249 offset:448
	s_waitcnt lgkmcnt(3)
	v_mfma_f32_16x16x32_bf16 v[36:39], v[0:3], v[148:151], v[36:39]
	v_mfma_f32_16x16x32_bf16 v[100:103], v[0:3], v[206:209], v[100:103]
	ds_read_b128 v[0:3], v249 offset:8448
	s_waitcnt lgkmcnt(3)
	v_mfma_f32_16x16x32_bf16 v[36:39], v[168:171], v[152:155], v[36:39]
	v_mfma_f32_16x16x32_bf16 v[100:103], v[168:171], v[224:227], v[100:103]
	ds_read_b128 v[168:171], v249 offset:8512
	s_waitcnt lgkmcnt(3)
	v_mfma_f32_16x16x32_bf16 v[36:39], v[172:175], v[156:159], v[36:39]
	v_mfma_f32_16x16x32_bf16 v[100:103], v[172:175], v[228:231], v[100:103]
	ds_read_b128 v[172:175], v249 offset:8576
	s_waitcnt lgkmcnt(3)
	v_mfma_f32_16x16x32_bf16 v[36:39], v[176:179], v[160:163], v[36:39]
	v_mfma_f32_16x16x32_bf16 v[100:103], v[176:179], v[232:235], v[100:103]
	ds_read_b128 v[176:179], v249 offset:8640
	s_waitcnt lgkmcnt(3)
	v_mfma_f32_16x16x32_bf16 v[40:43], v[0:3], v[132:135], 0
	v_mfma_f32_16x16x32_bf16 v[104:107], v[0:3], v[190:193], 0
	ds_read_b128 v[0:3], v249 offset:8704
	s_waitcnt lgkmcnt(3)
	v_mfma_f32_16x16x32_bf16 v[40:43], v[168:171], v[136:139], v[40:43]
	v_mfma_f32_16x16x32_bf16 v[104:107], v[168:171], v[194:197], v[104:107]
	ds_read_b128 v[168:171], v249 offset:8768
	s_waitcnt lgkmcnt(3)
	v_mfma_f32_16x16x32_bf16 v[40:43], v[172:175], v[140:143], v[40:43]
	v_mfma_f32_16x16x32_bf16 v[104:107], v[172:175], v[198:201], v[104:107]
	ds_read_b128 v[172:175], v249 offset:8832
	s_waitcnt lgkmcnt(3)
	v_mfma_f32_16x16x32_bf16 v[40:43], v[176:179], v[144:147], v[40:43]
	v_mfma_f32_16x16x32_bf16 v[104:107], v[176:179], v[202:205], v[104:107]
	ds_read_b128 v[176:179], v249 offset:8896
	s_waitcnt lgkmcnt(3)
	v_mfma_f32_16x16x32_bf16 v[40:43], v[0:3], v[148:151], v[40:43]
	v_mfma_f32_16x16x32_bf16 v[104:107], v[0:3], v[206:209], v[104:107]
	ds_read_b128 v[0:3], v249 offset:16896
	s_waitcnt lgkmcnt(3)
	v_mfma_f32_16x16x32_bf16 v[40:43], v[168:171], v[152:155], v[40:43]
	v_mfma_f32_16x16x32_bf16 v[104:107], v[168:171], v[224:227], v[104:107]
	ds_read_b128 v[168:171], v249 offset:16960
	s_waitcnt lgkmcnt(3)
	v_mfma_f32_16x16x32_bf16 v[40:43], v[172:175], v[156:159], v[40:43]
	v_mfma_f32_16x16x32_bf16 v[104:107], v[172:175], v[228:231], v[104:107]
	ds_read_b128 v[172:175], v249 offset:17024
	s_waitcnt lgkmcnt(3)
	v_mfma_f32_16x16x32_bf16 v[40:43], v[176:179], v[160:163], v[40:43]
	v_mfma_f32_16x16x32_bf16 v[104:107], v[176:179], v[232:235], v[104:107]
	ds_read_b128 v[176:179], v249 offset:17088
	s_waitcnt lgkmcnt(3)
	v_mfma_f32_16x16x32_bf16 v[44:47], v[0:3], v[132:135], 0
	v_mfma_f32_16x16x32_bf16 v[108:111], v[0:3], v[190:193], 0
	ds_read_b128 v[0:3], v249 offset:17152
	s_waitcnt lgkmcnt(3)
	v_mfma_f32_16x16x32_bf16 v[44:47], v[168:171], v[136:139], v[44:47]
	v_mfma_f32_16x16x32_bf16 v[108:111], v[168:171], v[194:197], v[108:111]
	ds_read_b128 v[168:171], v249 offset:17216
	s_waitcnt lgkmcnt(3)
	v_mfma_f32_16x16x32_bf16 v[44:47], v[172:175], v[140:143], v[44:47]
	v_mfma_f32_16x16x32_bf16 v[108:111], v[172:175], v[198:201], v[108:111]
	ds_read_b128 v[172:175], v249 offset:17280
	s_waitcnt lgkmcnt(3)
	v_mfma_f32_16x16x32_bf16 v[44:47], v[176:179], v[144:147], v[44:47]
	v_mfma_f32_16x16x32_bf16 v[108:111], v[176:179], v[202:205], v[108:111]
	ds_read_b128 v[176:179], v249 offset:17344
	s_waitcnt lgkmcnt(3)
	v_mfma_f32_16x16x32_bf16 v[44:47], v[0:3], v[148:151], v[44:47]
	v_mfma_f32_16x16x32_bf16 v[108:111], v[0:3], v[206:209], v[108:111]
	ds_read_b128 v[0:3], v249 offset:25344
	s_waitcnt lgkmcnt(3)
	v_mfma_f32_16x16x32_bf16 v[44:47], v[168:171], v[152:155], v[44:47]
	v_mfma_f32_16x16x32_bf16 v[108:111], v[168:171], v[224:227], v[108:111]
	ds_read_b128 v[168:171], v249 offset:25408
	s_waitcnt lgkmcnt(3)
	v_mfma_f32_16x16x32_bf16 v[44:47], v[172:175], v[156:159], v[44:47]
	v_mfma_f32_16x16x32_bf16 v[108:111], v[172:175], v[228:231], v[108:111]
	ds_read_b128 v[172:175], v249 offset:25472
	s_waitcnt lgkmcnt(3)
	v_mfma_f32_16x16x32_bf16 v[44:47], v[176:179], v[160:163], v[44:47]
	v_mfma_f32_16x16x32_bf16 v[108:111], v[176:179], v[232:235], v[108:111]
	ds_read_b128 v[176:179], v249 offset:25536
	s_waitcnt lgkmcnt(3)
	v_mfma_f32_16x16x32_bf16 v[48:51], v[0:3], v[132:135], 0
	v_mfma_f32_16x16x32_bf16 v[112:115], v[0:3], v[190:193], 0
	ds_read_b128 v[0:3], v249 offset:25600
	s_waitcnt lgkmcnt(3)
	v_mfma_f32_16x16x32_bf16 v[48:51], v[168:171], v[136:139], v[48:51]
	v_mfma_f32_16x16x32_bf16 v[112:115], v[168:171], v[194:197], v[112:115]
	ds_read_b128 v[168:171], v249 offset:25664
	s_waitcnt lgkmcnt(3)
	v_mfma_f32_16x16x32_bf16 v[48:51], v[172:175], v[140:143], v[48:51]
	v_mfma_f32_16x16x32_bf16 v[112:115], v[172:175], v[198:201], v[112:115]
	ds_read_b128 v[172:175], v249 offset:25728
	s_waitcnt lgkmcnt(3)
	v_mfma_f32_16x16x32_bf16 v[48:51], v[176:179], v[144:147], v[48:51]
	v_mfma_f32_16x16x32_bf16 v[112:115], v[176:179], v[202:205], v[112:115]
	ds_read_b128 v[176:179], v249 offset:25792
	s_waitcnt lgkmcnt(3)
	v_mfma_f32_16x16x32_bf16 v[48:51], v[0:3], v[148:151], v[48:51]
	v_mfma_f32_16x16x32_bf16 v[112:115], v[0:3], v[206:209], v[112:115]
	s_waitcnt lgkmcnt(2)
	v_mfma_f32_16x16x32_bf16 v[48:51], v[168:171], v[152:155], v[48:51]
	v_mfma_f32_16x16x32_bf16 v[112:115], v[168:171], v[224:227], v[112:115]
	s_waitcnt lgkmcnt(1)
	v_mfma_f32_16x16x32_bf16 v[48:51], v[172:175], v[156:159], v[48:51]
	v_mfma_f32_16x16x32_bf16 v[112:115], v[172:175], v[228:231], v[112:115]
	s_waitcnt lgkmcnt(0)
	v_mfma_f32_16x16x32_bf16 v[48:51], v[176:179], v[160:163], v[48:51]
	v_mfma_f32_16x16x32_bf16 v[112:115], v[176:179], v[232:235], v[112:115]
	s_waitcnt vmcnt(0)
	ds_write_b128 v187, v[236:239] offset:33792
	ds_write_b128 v187, v[240:243] offset:33920
	ds_write_b128 v187, v[164:167] offset:34048
	ds_write_b128 v187, v[182:185] offset:34176
	global_load_dwordx4 v[236:239], v[210:211], off offset:2048
	global_load_dwordx4 v[240:243], v[210:211], off offset:2176
	global_load_dwordx4 v[164:167], v[210:211], off offset:2304
	global_load_dwordx4 v[182:185], v[210:211], off offset:2432
	s_waitcnt lgkmcnt(0)
	s_barrier
	ds_read_b128 v[0:3], v249 offset:33792
	ds_read_b128 v[168:171], v249 offset:33856
	ds_read_b128 v[172:175], v249 offset:33920
	ds_read_b128 v[176:179], v249 offset:33984
	s_waitcnt lgkmcnt(3)
	v_mfma_f32_16x16x32_bf16 v[52:55], v[0:3], v[132:135], 0
	v_mfma_f32_16x16x32_bf16 v[116:119], v[0:3], v[190:193], 0
	ds_read_b128 v[0:3], v249 offset:34048
	s_waitcnt lgkmcnt(3)
	v_mfma_f32_16x16x32_bf16 v[52:55], v[168:171], v[136:139], v[52:55]
	v_mfma_f32_16x16x32_bf16 v[116:119], v[168:171], v[194:197], v[116:119]
	ds_read_b128 v[168:171], v249 offset:34112
	s_waitcnt lgkmcnt(3)
	v_mfma_f32_16x16x32_bf16 v[52:55], v[172:175], v[140:143], v[52:55]
	v_mfma_f32_16x16x32_bf16 v[116:119], v[172:175], v[198:201], v[116:119]
	ds_read_b128 v[172:175], v249 offset:34176
	s_waitcnt lgkmcnt(3)
	v_mfma_f32_16x16x32_bf16 v[52:55], v[176:179], v[144:147], v[52:55]
	v_mfma_f32_16x16x32_bf16 v[116:119], v[176:179], v[202:205], v[116:119]
	ds_read_b128 v[176:179], v249 offset:34240
	s_waitcnt lgkmcnt(3)
	v_mfma_f32_16x16x32_bf16 v[52:55], v[0:3], v[148:151], v[52:55]
	v_mfma_f32_16x16x32_bf16 v[116:119], v[0:3], v[206:209], v[116:119]
	ds_read_b128 v[0:3], v249 offset:42240
	s_waitcnt lgkmcnt(3)
	v_mfma_f32_16x16x32_bf16 v[52:55], v[168:171], v[152:155], v[52:55]
	v_mfma_f32_16x16x32_bf16 v[116:119], v[168:171], v[224:227], v[116:119]
	ds_read_b128 v[168:171], v249 offset:42304
	s_waitcnt lgkmcnt(3)
	v_mfma_f32_16x16x32_bf16 v[52:55], v[172:175], v[156:159], v[52:55]
	v_mfma_f32_16x16x32_bf16 v[116:119], v[172:175], v[228:231], v[116:119]
	ds_read_b128 v[172:175], v249 offset:42368
	s_waitcnt lgkmcnt(3)
	v_mfma_f32_16x16x32_bf16 v[52:55], v[176:179], v[160:163], v[52:55]
	v_mfma_f32_16x16x32_bf16 v[116:119], v[176:179], v[232:235], v[116:119]
	ds_read_b128 v[176:179], v249 offset:42432
	s_waitcnt lgkmcnt(3)
	v_mfma_f32_16x16x32_bf16 v[56:59], v[0:3], v[132:135], 0
	v_mfma_f32_16x16x32_bf16 v[120:123], v[0:3], v[190:193], 0
	ds_read_b128 v[0:3], v249 offset:42496
	s_waitcnt lgkmcnt(3)
	v_mfma_f32_16x16x32_bf16 v[56:59], v[168:171], v[136:139], v[56:59]
	v_mfma_f32_16x16x32_bf16 v[120:123], v[168:171], v[194:197], v[120:123]
	ds_read_b128 v[168:171], v249 offset:42560
	s_waitcnt lgkmcnt(3)
	v_mfma_f32_16x16x32_bf16 v[56:59], v[172:175], v[140:143], v[56:59]
	v_mfma_f32_16x16x32_bf16 v[120:123], v[172:175], v[198:201], v[120:123]
	ds_read_b128 v[172:175], v249 offset:42624
	s_waitcnt lgkmcnt(3)
	v_mfma_f32_16x16x32_bf16 v[56:59], v[176:179], v[144:147], v[56:59]
	v_mfma_f32_16x16x32_bf16 v[120:123], v[176:179], v[202:205], v[120:123]
	ds_read_b128 v[176:179], v249 offset:42688
	s_waitcnt lgkmcnt(3)
	v_mfma_f32_16x16x32_bf16 v[56:59], v[0:3], v[148:151], v[56:59]
	v_mfma_f32_16x16x32_bf16 v[120:123], v[0:3], v[206:209], v[120:123]
	ds_read_b128 v[0:3], v249 offset:50688
	s_waitcnt lgkmcnt(3)
	v_mfma_f32_16x16x32_bf16 v[56:59], v[168:171], v[152:155], v[56:59]
	v_mfma_f32_16x16x32_bf16 v[120:123], v[168:171], v[224:227], v[120:123]
	ds_read_b128 v[168:171], v249 offset:50752
	s_waitcnt lgkmcnt(3)
	v_mfma_f32_16x16x32_bf16 v[56:59], v[172:175], v[156:159], v[56:59]
	v_mfma_f32_16x16x32_bf16 v[120:123], v[172:175], v[228:231], v[120:123]
	ds_read_b128 v[172:175], v249 offset:50816
	s_waitcnt lgkmcnt(3)
	v_mfma_f32_16x16x32_bf16 v[56:59], v[176:179], v[160:163], v[56:59]
	v_mfma_f32_16x16x32_bf16 v[120:123], v[176:179], v[232:235], v[120:123]
	ds_read_b128 v[176:179], v249 offset:50880
	s_waitcnt lgkmcnt(3)
	v_mfma_f32_16x16x32_bf16 v[60:63], v[0:3], v[132:135], 0
	v_mfma_f32_16x16x32_bf16 v[124:127], v[0:3], v[190:193], 0
	ds_read_b128 v[0:3], v249 offset:50944
	s_waitcnt lgkmcnt(3)
	v_mfma_f32_16x16x32_bf16 v[60:63], v[168:171], v[136:139], v[60:63]
	v_mfma_f32_16x16x32_bf16 v[124:127], v[168:171], v[194:197], v[124:127]
	ds_read_b128 v[168:171], v249 offset:51008
	s_waitcnt lgkmcnt(3)
	v_mfma_f32_16x16x32_bf16 v[60:63], v[172:175], v[140:143], v[60:63]
	v_mfma_f32_16x16x32_bf16 v[124:127], v[172:175], v[198:201], v[124:127]
	ds_read_b128 v[172:175], v249 offset:51072
	s_waitcnt lgkmcnt(3)
	v_mfma_f32_16x16x32_bf16 v[60:63], v[176:179], v[144:147], v[60:63]
	v_mfma_f32_16x16x32_bf16 v[124:127], v[176:179], v[202:205], v[124:127]
	ds_read_b128 v[176:179], v249 offset:51136
	s_waitcnt lgkmcnt(3)
	v_mfma_f32_16x16x32_bf16 v[60:63], v[0:3], v[148:151], v[60:63]
	v_mfma_f32_16x16x32_bf16 v[124:127], v[0:3], v[206:209], v[124:127]
	ds_read_b128 v[0:3], v249 offset:59136
	s_waitcnt lgkmcnt(3)
	v_mfma_f32_16x16x32_bf16 v[60:63], v[168:171], v[152:155], v[60:63]
	v_mfma_f32_16x16x32_bf16 v[124:127], v[168:171], v[224:227], v[124:127]
	ds_read_b128 v[168:171], v249 offset:59200
	s_waitcnt lgkmcnt(3)
	v_mfma_f32_16x16x32_bf16 v[60:63], v[172:175], v[156:159], v[60:63]
	v_mfma_f32_16x16x32_bf16 v[124:127], v[172:175], v[228:231], v[124:127]
	ds_read_b128 v[172:175], v249 offset:59264
	s_waitcnt lgkmcnt(3)
	v_mfma_f32_16x16x32_bf16 v[60:63], v[176:179], v[160:163], v[60:63]
	v_mfma_f32_16x16x32_bf16 v[124:127], v[176:179], v[232:235], v[124:127]
	ds_read_b128 v[176:179], v249 offset:59328
	s_waitcnt lgkmcnt(3)
	v_mfma_f32_16x16x32_bf16 v[64:67], v[0:3], v[132:135], 0
	v_mfma_f32_16x16x32_bf16 v[128:131], v[0:3], v[190:193], 0
	ds_read_b128 v[0:3], v249 offset:59392
	s_waitcnt lgkmcnt(3)
	v_mfma_f32_16x16x32_bf16 v[64:67], v[168:171], v[136:139], v[64:67]
	v_mfma_f32_16x16x32_bf16 v[128:131], v[168:171], v[194:197], v[128:131]
	ds_read_b128 v[168:171], v249 offset:59456
	s_waitcnt lgkmcnt(3)
	v_mfma_f32_16x16x32_bf16 v[64:67], v[172:175], v[140:143], v[64:67]
	v_mfma_f32_16x16x32_bf16 v[128:131], v[172:175], v[198:201], v[128:131]
	ds_read_b128 v[172:175], v249 offset:59520
	s_waitcnt lgkmcnt(3)
	v_mfma_f32_16x16x32_bf16 v[64:67], v[176:179], v[144:147], v[64:67]
	v_mfma_f32_16x16x32_bf16 v[128:131], v[176:179], v[202:205], v[128:131]
	ds_read_b128 v[176:179], v249 offset:59584
	s_waitcnt lgkmcnt(3)
	v_mfma_f32_16x16x32_bf16 v[64:67], v[0:3], v[148:151], v[64:67]
	v_mfma_f32_16x16x32_bf16 v[128:131], v[0:3], v[206:209], v[128:131]
	s_waitcnt lgkmcnt(2)
	v_mfma_f32_16x16x32_bf16 v[64:67], v[168:171], v[152:155], v[64:67]
	v_mfma_f32_16x16x32_bf16 v[128:131], v[168:171], v[224:227], v[128:131]
	s_waitcnt lgkmcnt(1)
	v_mfma_f32_16x16x32_bf16 v[64:67], v[172:175], v[156:159], v[64:67]
	v_mfma_f32_16x16x32_bf16 v[128:131], v[172:175], v[228:231], v[128:131]
	s_waitcnt lgkmcnt(0)
	v_mfma_f32_16x16x32_bf16 v[64:67], v[176:179], v[160:163], v[64:67]
	v_mfma_f32_16x16x32_bf16 v[128:131], v[176:179], v[232:235], v[128:131]
	s_nop 7
	s_nop 1
	s_mov_b32 s7, 0xf149f2ca
	v_max3_f32 v168, v4, v5, v6
	v_max3_f32 v168, v168, v7, v8
	v_max3_f32 v168, v168, v9, v10
	v_max3_f32 v168, v168, v11, v12
	v_max3_f32 v168, v168, v13, v14
	v_max3_f32 v168, v168, v15, v16
	v_max3_f32 v168, v168, v17, v18
	v_max3_f32 v168, v168, v19, v20
	v_max3_f32 v168, v168, v21, v22
	v_max3_f32 v168, v168, v23, v24
	v_max3_f32 v168, v168, v25, v26
	v_max3_f32 v168, v168, v27, v28
	v_max3_f32 v168, v168, v29, v30
	v_max3_f32 v168, v168, v31, v32
	v_max3_f32 v168, v168, v33, v34
	v_max3_f32 v168, v168, v35, v36
	v_max3_f32 v168, v168, v37, v38
	v_max3_f32 v168, v168, v39, v40
	v_max3_f32 v168, v168, v41, v42
	v_max3_f32 v168, v168, v43, v44
	v_max3_f32 v168, v168, v45, v46
	v_max3_f32 v168, v168, v47, v48
	v_max3_f32 v168, v168, v49, v50
	v_max3_f32 v168, v168, v51, v52
	v_max3_f32 v168, v168, v53, v54
	v_max3_f32 v168, v168, v55, v56
	v_max3_f32 v168, v168, v57, v58
	v_max3_f32 v168, v168, v59, v60
	v_max3_f32 v168, v168, v61, v62
	v_max3_f32 v168, v168, v63, v64
	v_max3_f32 v168, v168, v65, v66
	v_max3_f32 v168, v168, s7, v67
	ds_bpermute_b32 v169, v189, v168
	s_waitcnt lgkmcnt(0)
	v_max_f32_e32 v168, v168, v169
	ds_bpermute_b32 v169, v222, v168
	s_waitcnt lgkmcnt(0)
	v_max_f32_e32 v168, v168, v169
	v_sub_f32_e32 v0, v4, v168
	v_sub_f32_e32 v1, v5, v168
	v_sub_f32_e32 v2, v6, v168
	v_sub_f32_e32 v3, v7, v168
	v_mul_f32_e32 v0, 0x3d800000, v0
	v_mul_f32_e32 v1, 0x3d800000, v1
	v_mul_f32_e32 v2, 0x3d800000, v2
	v_mul_f32_e32 v3, 0x3d800000, v3
	v_mul_f32_e32 v0, 0x3fb8aa3b, v0
	v_mul_f32_e32 v1, 0x3fb8aa3b, v1
	v_mul_f32_e32 v2, 0x3fb8aa3b, v2
	v_mul_f32_e32 v3, 0x3fb8aa3b, v3
	v_exp_f32_e32 v4, v0
	v_exp_f32_e32 v5, v1
	v_exp_f32_e32 v6, v2
	v_exp_f32_e32 v7, v3
	v_add_f32_e32 v220, 0, v4
	v_add_f32_e32 v220, v5, v220
	v_add_f32_e32 v220, v6, v220
	v_add_f32_e32 v220, v7, v220
	v_sub_f32_e32 v0, v8, v168
	v_sub_f32_e32 v1, v9, v168
	v_sub_f32_e32 v2, v10, v168
	v_sub_f32_e32 v3, v11, v168
	v_mul_f32_e32 v0, 0x3d800000, v0
	v_mul_f32_e32 v1, 0x3d800000, v1
	v_mul_f32_e32 v2, 0x3d800000, v2
	v_mul_f32_e32 v3, 0x3d800000, v3
	v_mul_f32_e32 v0, 0x3fb8aa3b, v0
	v_mul_f32_e32 v1, 0x3fb8aa3b, v1
	v_mul_f32_e32 v2, 0x3fb8aa3b, v2
	v_mul_f32_e32 v3, 0x3fb8aa3b, v3
	v_exp_f32_e32 v8, v0
	v_exp_f32_e32 v9, v1
	v_exp_f32_e32 v10, v2
	v_exp_f32_e32 v11, v3
	v_add_f32_e32 v220, v8, v220
	v_add_f32_e32 v220, v9, v220
	v_add_f32_e32 v220, v10, v220
	v_add_f32_e32 v220, v11, v220
	v_cvt_pk_bf16_f32 v132, v4, v5
	v_cvt_pk_bf16_f32 v133, v6, v7
	v_cvt_pk_bf16_f32 v134, v8, v9
	v_cvt_pk_bf16_f32 v135, v10, v11
	v_sub_f32_e32 v0, v12, v168
	v_sub_f32_e32 v1, v13, v168
	v_sub_f32_e32 v2, v14, v168
	v_sub_f32_e32 v3, v15, v168
	v_mul_f32_e32 v0, 0x3d800000, v0
	v_mul_f32_e32 v1, 0x3d800000, v1
	v_mul_f32_e32 v2, 0x3d800000, v2
	v_mul_f32_e32 v3, 0x3d800000, v3
	v_mul_f32_e32 v0, 0x3fb8aa3b, v0
	v_mul_f32_e32 v1, 0x3fb8aa3b, v1
	v_mul_f32_e32 v2, 0x3fb8aa3b, v2
	v_mul_f32_e32 v3, 0x3fb8aa3b, v3
	v_exp_f32_e32 v12, v0
	v_exp_f32_e32 v13, v1
	v_exp_f32_e32 v14, v2
	v_exp_f32_e32 v15, v3
	v_add_f32_e32 v220, v12, v220
	v_add_f32_e32 v220, v13, v220
	v_add_f32_e32 v220, v14, v220
	v_add_f32_e32 v220, v15, v220
	v_sub_f32_e32 v0, v16, v168
	v_sub_f32_e32 v1, v17, v168
	v_sub_f32_e32 v2, v18, v168
	v_sub_f32_e32 v3, v19, v168
	v_mul_f32_e32 v0, 0x3d800000, v0
	v_mul_f32_e32 v1, 0x3d800000, v1
	v_mul_f32_e32 v2, 0x3d800000, v2
	v_mul_f32_e32 v3, 0x3d800000, v3
	v_mul_f32_e32 v0, 0x3fb8aa3b, v0
	v_mul_f32_e32 v1, 0x3fb8aa3b, v1
	v_mul_f32_e32 v2, 0x3fb8aa3b, v2
	v_mul_f32_e32 v3, 0x3fb8aa3b, v3
	v_exp_f32_e32 v16, v0
	v_exp_f32_e32 v17, v1
	v_exp_f32_e32 v18, v2
	v_exp_f32_e32 v19, v3
	v_add_f32_e32 v220, v16, v220
	v_add_f32_e32 v220, v17, v220
	v_add_f32_e32 v220, v18, v220
	v_add_f32_e32 v220, v19, v220
	v_cvt_pk_bf16_f32 v136, v12, v13
	v_cvt_pk_bf16_f32 v137, v14, v15
	v_cvt_pk_bf16_f32 v138, v16, v17
	v_cvt_pk_bf16_f32 v139, v18, v19
	v_sub_f32_e32 v0, v20, v168
	v_sub_f32_e32 v1, v21, v168
	v_sub_f32_e32 v2, v22, v168
	v_sub_f32_e32 v3, v23, v168
	v_mul_f32_e32 v0, 0x3d800000, v0
	v_mul_f32_e32 v1, 0x3d800000, v1
	v_mul_f32_e32 v2, 0x3d800000, v2
	v_mul_f32_e32 v3, 0x3d800000, v3
	v_mul_f32_e32 v0, 0x3fb8aa3b, v0
	v_mul_f32_e32 v1, 0x3fb8aa3b, v1
	v_mul_f32_e32 v2, 0x3fb8aa3b, v2
	v_mul_f32_e32 v3, 0x3fb8aa3b, v3
	v_exp_f32_e32 v20, v0
	v_exp_f32_e32 v21, v1
	v_exp_f32_e32 v22, v2
	v_exp_f32_e32 v23, v3
	v_add_f32_e32 v220, v20, v220
	v_add_f32_e32 v220, v21, v220
	v_add_f32_e32 v220, v22, v220
	v_add_f32_e32 v220, v23, v220
	v_sub_f32_e32 v0, v24, v168
	v_sub_f32_e32 v1, v25, v168
	v_sub_f32_e32 v2, v26, v168
	v_sub_f32_e32 v3, v27, v168
	v_mul_f32_e32 v0, 0x3d800000, v0
	v_mul_f32_e32 v1, 0x3d800000, v1
	v_mul_f32_e32 v2, 0x3d800000, v2
	v_mul_f32_e32 v3, 0x3d800000, v3
	v_mul_f32_e32 v0, 0x3fb8aa3b, v0
	v_mul_f32_e32 v1, 0x3fb8aa3b, v1
	v_mul_f32_e32 v2, 0x3fb8aa3b, v2
	v_mul_f32_e32 v3, 0x3fb8aa3b, v3
	v_exp_f32_e32 v24, v0
	v_exp_f32_e32 v25, v1
	v_exp_f32_e32 v26, v2
	v_exp_f32_e32 v27, v3
	v_add_f32_e32 v220, v24, v220
	v_add_f32_e32 v220, v25, v220
	v_add_f32_e32 v220, v26, v220
	v_add_f32_e32 v220, v27, v220
	v_cvt_pk_bf16_f32 v140, v20, v21
	v_cvt_pk_bf16_f32 v141, v22, v23
	v_cvt_pk_bf16_f32 v142, v24, v25
	v_cvt_pk_bf16_f32 v143, v26, v27
	v_sub_f32_e32 v0, v28, v168
	v_sub_f32_e32 v1, v29, v168
	v_sub_f32_e32 v2, v30, v168
	v_sub_f32_e32 v3, v31, v168
	v_mul_f32_e32 v0, 0x3d800000, v0
	v_mul_f32_e32 v1, 0x3d800000, v1
	v_mul_f32_e32 v2, 0x3d800000, v2
	v_mul_f32_e32 v3, 0x3d800000, v3
	v_mul_f32_e32 v0, 0x3fb8aa3b, v0
	v_mul_f32_e32 v1, 0x3fb8aa3b, v1
	v_mul_f32_e32 v2, 0x3fb8aa3b, v2
	v_mul_f32_e32 v3, 0x3fb8aa3b, v3
	v_exp_f32_e32 v28, v0
	v_exp_f32_e32 v29, v1
	v_exp_f32_e32 v30, v2
	v_exp_f32_e32 v31, v3
	v_add_f32_e32 v220, v28, v220
	v_add_f32_e32 v220, v29, v220
	v_add_f32_e32 v220, v30, v220
	v_add_f32_e32 v220, v31, v220
	v_sub_f32_e32 v0, v32, v168
	v_sub_f32_e32 v1, v33, v168
	v_sub_f32_e32 v2, v34, v168
	v_sub_f32_e32 v3, v35, v168
	v_mul_f32_e32 v0, 0x3d800000, v0
	v_mul_f32_e32 v1, 0x3d800000, v1
	v_mul_f32_e32 v2, 0x3d800000, v2
	v_mul_f32_e32 v3, 0x3d800000, v3
	v_mul_f32_e32 v0, 0x3fb8aa3b, v0
	v_mul_f32_e32 v1, 0x3fb8aa3b, v1
	v_mul_f32_e32 v2, 0x3fb8aa3b, v2
	v_mul_f32_e32 v3, 0x3fb8aa3b, v3
	v_exp_f32_e32 v32, v0
	v_exp_f32_e32 v33, v1
	v_exp_f32_e32 v34, v2
	v_exp_f32_e32 v35, v3
	v_add_f32_e32 v220, v32, v220
	v_add_f32_e32 v220, v33, v220
	v_add_f32_e32 v220, v34, v220
	v_add_f32_e32 v220, v35, v220
	v_cvt_pk_bf16_f32 v144, v28, v29
	v_cvt_pk_bf16_f32 v145, v30, v31
	v_cvt_pk_bf16_f32 v146, v32, v33
	v_cvt_pk_bf16_f32 v147, v34, v35
	v_sub_f32_e32 v0, v36, v168
	v_sub_f32_e32 v1, v37, v168
	v_sub_f32_e32 v2, v38, v168
	v_sub_f32_e32 v3, v39, v168
	v_mul_f32_e32 v0, 0x3d800000, v0
	v_mul_f32_e32 v1, 0x3d800000, v1
	v_mul_f32_e32 v2, 0x3d800000, v2
	v_mul_f32_e32 v3, 0x3d800000, v3
	v_mul_f32_e32 v0, 0x3fb8aa3b, v0
	v_mul_f32_e32 v1, 0x3fb8aa3b, v1
	v_mul_f32_e32 v2, 0x3fb8aa3b, v2
	v_mul_f32_e32 v3, 0x3fb8aa3b, v3
	v_exp_f32_e32 v36, v0
	v_exp_f32_e32 v37, v1
	v_exp_f32_e32 v38, v2
	v_exp_f32_e32 v39, v3
	v_add_f32_e32 v220, v36, v220
	v_add_f32_e32 v220, v37, v220
	v_add_f32_e32 v220, v38, v220
	v_add_f32_e32 v220, v39, v220
	v_sub_f32_e32 v0, v40, v168
	v_sub_f32_e32 v1, v41, v168
	v_sub_f32_e32 v2, v42, v168
	v_sub_f32_e32 v3, v43, v168
	v_mul_f32_e32 v0, 0x3d800000, v0
	v_mul_f32_e32 v1, 0x3d800000, v1
	v_mul_f32_e32 v2, 0x3d800000, v2
	v_mul_f32_e32 v3, 0x3d800000, v3
	v_mul_f32_e32 v0, 0x3fb8aa3b, v0
	v_mul_f32_e32 v1, 0x3fb8aa3b, v1
	v_mul_f32_e32 v2, 0x3fb8aa3b, v2
	v_mul_f32_e32 v3, 0x3fb8aa3b, v3
	v_exp_f32_e32 v40, v0
	v_exp_f32_e32 v41, v1
	v_exp_f32_e32 v42, v2
	v_exp_f32_e32 v43, v3
	v_add_f32_e32 v220, v40, v220
	v_add_f32_e32 v220, v41, v220
	v_add_f32_e32 v220, v42, v220
	v_add_f32_e32 v220, v43, v220
	v_cvt_pk_bf16_f32 v148, v36, v37
	v_cvt_pk_bf16_f32 v149, v38, v39
	v_cvt_pk_bf16_f32 v150, v40, v41
	v_cvt_pk_bf16_f32 v151, v42, v43
	v_sub_f32_e32 v0, v44, v168
	v_sub_f32_e32 v1, v45, v168
	v_sub_f32_e32 v2, v46, v168
	v_sub_f32_e32 v3, v47, v168
	v_mul_f32_e32 v0, 0x3d800000, v0
	v_mul_f32_e32 v1, 0x3d800000, v1
	v_mul_f32_e32 v2, 0x3d800000, v2
	v_mul_f32_e32 v3, 0x3d800000, v3
	v_mul_f32_e32 v0, 0x3fb8aa3b, v0
	v_mul_f32_e32 v1, 0x3fb8aa3b, v1
	v_mul_f32_e32 v2, 0x3fb8aa3b, v2
	v_mul_f32_e32 v3, 0x3fb8aa3b, v3
	v_exp_f32_e32 v44, v0
	v_exp_f32_e32 v45, v1
	v_exp_f32_e32 v46, v2
	v_exp_f32_e32 v47, v3
	v_add_f32_e32 v220, v44, v220
	v_add_f32_e32 v220, v45, v220
	v_add_f32_e32 v220, v46, v220
	v_add_f32_e32 v220, v47, v220
	v_sub_f32_e32 v0, v48, v168
	v_sub_f32_e32 v1, v49, v168
	v_sub_f32_e32 v2, v50, v168
	v_sub_f32_e32 v3, v51, v168
	v_mul_f32_e32 v0, 0x3d800000, v0
	v_mul_f32_e32 v1, 0x3d800000, v1
	v_mul_f32_e32 v2, 0x3d800000, v2
	v_mul_f32_e32 v3, 0x3d800000, v3
	v_mul_f32_e32 v0, 0x3fb8aa3b, v0
	v_mul_f32_e32 v1, 0x3fb8aa3b, v1
	v_mul_f32_e32 v2, 0x3fb8aa3b, v2
	v_mul_f32_e32 v3, 0x3fb8aa3b, v3
	v_exp_f32_e32 v48, v0
	v_exp_f32_e32 v49, v1
	v_exp_f32_e32 v50, v2
	v_exp_f32_e32 v51, v3
	v_add_f32_e32 v220, v48, v220
	v_add_f32_e32 v220, v49, v220
	v_add_f32_e32 v220, v50, v220
	v_add_f32_e32 v220, v51, v220
	v_cvt_pk_bf16_f32 v152, v44, v45
	v_cvt_pk_bf16_f32 v153, v46, v47
	v_cvt_pk_bf16_f32 v154, v48, v49
	v_cvt_pk_bf16_f32 v155, v50, v51
	v_sub_f32_e32 v0, v52, v168
	v_sub_f32_e32 v1, v53, v168
	v_sub_f32_e32 v2, v54, v168
	v_sub_f32_e32 v3, v55, v168
	v_mul_f32_e32 v0, 0x3d800000, v0
	v_mul_f32_e32 v1, 0x3d800000, v1
	v_mul_f32_e32 v2, 0x3d800000, v2
	v_mul_f32_e32 v3, 0x3d800000, v3
	v_mul_f32_e32 v0, 0x3fb8aa3b, v0
	v_mul_f32_e32 v1, 0x3fb8aa3b, v1
	v_mul_f32_e32 v2, 0x3fb8aa3b, v2
	v_mul_f32_e32 v3, 0x3fb8aa3b, v3
	v_exp_f32_e32 v52, v0
	v_exp_f32_e32 v53, v1
	v_exp_f32_e32 v54, v2
	v_exp_f32_e32 v55, v3
	v_add_f32_e32 v220, v52, v220
	v_add_f32_e32 v220, v53, v220
	v_add_f32_e32 v220, v54, v220
	v_add_f32_e32 v220, v55, v220
	v_sub_f32_e32 v0, v56, v168
	v_sub_f32_e32 v1, v57, v168
	v_sub_f32_e32 v2, v58, v168
	v_sub_f32_e32 v3, v59, v168
	v_mul_f32_e32 v0, 0x3d800000, v0
	v_mul_f32_e32 v1, 0x3d800000, v1
	v_mul_f32_e32 v2, 0x3d800000, v2
	v_mul_f32_e32 v3, 0x3d800000, v3
	v_mul_f32_e32 v0, 0x3fb8aa3b, v0
	v_mul_f32_e32 v1, 0x3fb8aa3b, v1
	v_mul_f32_e32 v2, 0x3fb8aa3b, v2
	v_mul_f32_e32 v3, 0x3fb8aa3b, v3
	v_exp_f32_e32 v56, v0
	v_exp_f32_e32 v57, v1
	v_exp_f32_e32 v58, v2
	v_exp_f32_e32 v59, v3
	v_add_f32_e32 v220, v56, v220
	v_add_f32_e32 v220, v57, v220
	v_add_f32_e32 v220, v58, v220
	v_add_f32_e32 v220, v59, v220
	v_cvt_pk_bf16_f32 v156, v52, v53
	v_cvt_pk_bf16_f32 v157, v54, v55
	v_cvt_pk_bf16_f32 v158, v56, v57
	v_cvt_pk_bf16_f32 v159, v58, v59
	v_sub_f32_e32 v0, v60, v168
	v_sub_f32_e32 v1, v61, v168
	v_sub_f32_e32 v2, v62, v168
	v_sub_f32_e32 v3, v63, v168
	v_mul_f32_e32 v0, 0x3d800000, v0
	v_mul_f32_e32 v1, 0x3d800000, v1
	v_mul_f32_e32 v2, 0x3d800000, v2
	v_mul_f32_e32 v3, 0x3d800000, v3
	v_mul_f32_e32 v0, 0x3fb8aa3b, v0
	v_mul_f32_e32 v1, 0x3fb8aa3b, v1
	v_mul_f32_e32 v2, 0x3fb8aa3b, v2
	v_mul_f32_e32 v3, 0x3fb8aa3b, v3
	v_exp_f32_e32 v60, v0
	v_exp_f32_e32 v61, v1
	v_exp_f32_e32 v62, v2
	v_exp_f32_e32 v63, v3
	v_add_f32_e32 v220, v60, v220
	v_add_f32_e32 v220, v61, v220
	v_add_f32_e32 v220, v62, v220
	v_add_f32_e32 v220, v63, v220
	v_sub_f32_e32 v0, v64, v168
	v_sub_f32_e32 v1, v65, v168
	v_sub_f32_e32 v2, v66, v168
	v_sub_f32_e32 v3, v67, v168
	v_mul_f32_e32 v0, 0x3d800000, v0
	v_mul_f32_e32 v1, 0x3d800000, v1
	v_mul_f32_e32 v2, 0x3d800000, v2
	v_mul_f32_e32 v3, 0x3d800000, v3
	v_mul_f32_e32 v0, 0x3fb8aa3b, v0
	v_mul_f32_e32 v1, 0x3fb8aa3b, v1
	v_mul_f32_e32 v2, 0x3fb8aa3b, v2
	v_mul_f32_e32 v3, 0x3fb8aa3b, v3
	v_exp_f32_e32 v64, v0
	v_exp_f32_e32 v65, v1
	v_exp_f32_e32 v66, v2
	v_exp_f32_e32 v67, v3
	v_add_f32_e32 v220, v64, v220
	v_add_f32_e32 v220, v65, v220
	v_add_f32_e32 v220, v66, v220
	v_add_f32_e32 v220, v67, v220
	v_cvt_pk_bf16_f32 v160, v60, v61
	v_cvt_pk_bf16_f32 v161, v62, v63
	v_cvt_pk_bf16_f32 v162, v64, v65
	v_cvt_pk_bf16_f32 v163, v66, v67
	ds_bpermute_b32 v169, v189, v220
	s_waitcnt lgkmcnt(0)
	v_add_f32_e32 v220, v220, v169
	ds_bpermute_b32 v169, v222, v220
	s_waitcnt lgkmcnt(0)
	v_add_f32_e32 v220, v220, v169
	v_max3_f32 v168, v68, v69, v70
	v_max3_f32 v168, v168, v71, v72
	v_max3_f32 v168, v168, v73, v74
	v_max3_f32 v168, v168, v75, v76
	v_max3_f32 v168, v168, v77, v78
	v_max3_f32 v168, v168, v79, v80
	v_max3_f32 v168, v168, v81, v82
	v_max3_f32 v168, v168, v83, v84
	v_max3_f32 v168, v168, v85, v86
	v_max3_f32 v168, v168, v87, v88
	v_max3_f32 v168, v168, v89, v90
	v_max3_f32 v168, v168, v91, v92
	v_max3_f32 v168, v168, v93, v94
	v_max3_f32 v168, v168, v95, v96
	v_max3_f32 v168, v168, v97, v98
	v_max3_f32 v168, v168, v99, v100
	v_max3_f32 v168, v168, v101, v102
	v_max3_f32 v168, v168, v103, v104
	v_max3_f32 v168, v168, v105, v106
	v_max3_f32 v168, v168, v107, v108
	v_max3_f32 v168, v168, v109, v110
	v_max3_f32 v168, v168, v111, v112
	v_max3_f32 v168, v168, v113, v114
	v_max3_f32 v168, v168, v115, v116
	v_max3_f32 v168, v168, v117, v118
	v_max3_f32 v168, v168, v119, v120
	v_max3_f32 v168, v168, v121, v122
	v_max3_f32 v168, v168, v123, v124
	v_max3_f32 v168, v168, v125, v126
	v_max3_f32 v168, v168, v127, v128
	v_max3_f32 v168, v168, v129, v130
	v_max3_f32 v168, v168, s7, v131
	ds_bpermute_b32 v169, v189, v168
	s_waitcnt lgkmcnt(0)
	v_max_f32_e32 v168, v168, v169
	ds_bpermute_b32 v169, v222, v168
	s_waitcnt lgkmcnt(0)
	v_max_f32_e32 v168, v168, v169
	v_sub_f32_e32 v0, v68, v168
	v_sub_f32_e32 v1, v69, v168
	v_sub_f32_e32 v2, v70, v168
	v_sub_f32_e32 v3, v71, v168
	v_mul_f32_e32 v0, 0x3d800000, v0
	v_mul_f32_e32 v1, 0x3d800000, v1
	v_mul_f32_e32 v2, 0x3d800000, v2
	v_mul_f32_e32 v3, 0x3d800000, v3
	v_mul_f32_e32 v0, 0x3fb8aa3b, v0
	v_mul_f32_e32 v1, 0x3fb8aa3b, v1
	v_mul_f32_e32 v2, 0x3fb8aa3b, v2
	v_mul_f32_e32 v3, 0x3fb8aa3b, v3
	v_exp_f32_e32 v68, v0
	v_exp_f32_e32 v69, v1
	v_exp_f32_e32 v70, v2
	v_exp_f32_e32 v71, v3
	v_add_f32_e32 v221, 0, v68
	v_add_f32_e32 v221, v69, v221
	v_add_f32_e32 v221, v70, v221
	v_add_f32_e32 v221, v71, v221
	v_sub_f32_e32 v0, v72, v168
	v_sub_f32_e32 v1, v73, v168
	v_sub_f32_e32 v2, v74, v168
	v_sub_f32_e32 v3, v75, v168
	v_mul_f32_e32 v0, 0x3d800000, v0
	v_mul_f32_e32 v1, 0x3d800000, v1
	v_mul_f32_e32 v2, 0x3d800000, v2
	v_mul_f32_e32 v3, 0x3d800000, v3
	v_mul_f32_e32 v0, 0x3fb8aa3b, v0
	v_mul_f32_e32 v1, 0x3fb8aa3b, v1
	v_mul_f32_e32 v2, 0x3fb8aa3b, v2
	v_mul_f32_e32 v3, 0x3fb8aa3b, v3
	v_exp_f32_e32 v72, v0
	v_exp_f32_e32 v73, v1
	v_exp_f32_e32 v74, v2
	v_exp_f32_e32 v75, v3
	v_add_f32_e32 v221, v72, v221
	v_add_f32_e32 v221, v73, v221
	v_add_f32_e32 v221, v74, v221
	v_add_f32_e32 v221, v75, v221
	v_cvt_pk_bf16_f32 v190, v68, v69
	v_cvt_pk_bf16_f32 v191, v70, v71
	v_cvt_pk_bf16_f32 v192, v72, v73
	v_cvt_pk_bf16_f32 v193, v74, v75
	v_sub_f32_e32 v0, v76, v168
	v_sub_f32_e32 v1, v77, v168
	v_sub_f32_e32 v2, v78, v168
	v_sub_f32_e32 v3, v79, v168
	v_mul_f32_e32 v0, 0x3d800000, v0
	v_mul_f32_e32 v1, 0x3d800000, v1
	v_mul_f32_e32 v2, 0x3d800000, v2
	v_mul_f32_e32 v3, 0x3d800000, v3
	v_mul_f32_e32 v0, 0x3fb8aa3b, v0
	v_mul_f32_e32 v1, 0x3fb8aa3b, v1
	v_mul_f32_e32 v2, 0x3fb8aa3b, v2
	v_mul_f32_e32 v3, 0x3fb8aa3b, v3
	v_exp_f32_e32 v76, v0
	v_exp_f32_e32 v77, v1
	v_exp_f32_e32 v78, v2
	v_exp_f32_e32 v79, v3
	v_add_f32_e32 v221, v76, v221
	v_add_f32_e32 v221, v77, v221
	v_add_f32_e32 v221, v78, v221
	v_add_f32_e32 v221, v79, v221
	v_sub_f32_e32 v0, v80, v168
	v_sub_f32_e32 v1, v81, v168
	v_sub_f32_e32 v2, v82, v168
	v_sub_f32_e32 v3, v83, v168
	v_mul_f32_e32 v0, 0x3d800000, v0
	v_mul_f32_e32 v1, 0x3d800000, v1
	v_mul_f32_e32 v2, 0x3d800000, v2
	v_mul_f32_e32 v3, 0x3d800000, v3
	v_mul_f32_e32 v0, 0x3fb8aa3b, v0
	v_mul_f32_e32 v1, 0x3fb8aa3b, v1
	v_mul_f32_e32 v2, 0x3fb8aa3b, v2
	v_mul_f32_e32 v3, 0x3fb8aa3b, v3
	v_exp_f32_e32 v80, v0
	v_exp_f32_e32 v81, v1
	v_exp_f32_e32 v82, v2
	v_exp_f32_e32 v83, v3
	v_add_f32_e32 v221, v80, v221
	v_add_f32_e32 v221, v81, v221
	v_add_f32_e32 v221, v82, v221
	v_add_f32_e32 v221, v83, v221
	v_cvt_pk_bf16_f32 v194, v76, v77
	v_cvt_pk_bf16_f32 v195, v78, v79
	v_cvt_pk_bf16_f32 v196, v80, v81
	v_cvt_pk_bf16_f32 v197, v82, v83
	v_sub_f32_e32 v0, v84, v168
	v_sub_f32_e32 v1, v85, v168
	v_sub_f32_e32 v2, v86, v168
	v_sub_f32_e32 v3, v87, v168
	v_mul_f32_e32 v0, 0x3d800000, v0
	v_mul_f32_e32 v1, 0x3d800000, v1
	v_mul_f32_e32 v2, 0x3d800000, v2
	v_mul_f32_e32 v3, 0x3d800000, v3
	v_mul_f32_e32 v0, 0x3fb8aa3b, v0
	v_mul_f32_e32 v1, 0x3fb8aa3b, v1
	v_mul_f32_e32 v2, 0x3fb8aa3b, v2
	v_mul_f32_e32 v3, 0x3fb8aa3b, v3
	v_exp_f32_e32 v84, v0
	v_exp_f32_e32 v85, v1
	v_exp_f32_e32 v86, v2
	v_exp_f32_e32 v87, v3
	v_add_f32_e32 v221, v84, v221
	v_add_f32_e32 v221, v85, v221
	v_add_f32_e32 v221, v86, v221
	v_add_f32_e32 v221, v87, v221
	v_sub_f32_e32 v0, v88, v168
	v_sub_f32_e32 v1, v89, v168
	v_sub_f32_e32 v2, v90, v168
	v_sub_f32_e32 v3, v91, v168
	v_mul_f32_e32 v0, 0x3d800000, v0
	v_mul_f32_e32 v1, 0x3d800000, v1
	v_mul_f32_e32 v2, 0x3d800000, v2
	v_mul_f32_e32 v3, 0x3d800000, v3
	v_mul_f32_e32 v0, 0x3fb8aa3b, v0
	v_mul_f32_e32 v1, 0x3fb8aa3b, v1
	v_mul_f32_e32 v2, 0x3fb8aa3b, v2
	v_mul_f32_e32 v3, 0x3fb8aa3b, v3
	v_exp_f32_e32 v88, v0
	v_exp_f32_e32 v89, v1
	v_exp_f32_e32 v90, v2
	v_exp_f32_e32 v91, v3
	v_add_f32_e32 v221, v88, v221
	v_add_f32_e32 v221, v89, v221
	v_add_f32_e32 v221, v90, v221
	v_add_f32_e32 v221, v91, v221
	v_cvt_pk_bf16_f32 v198, v84, v85
	v_cvt_pk_bf16_f32 v199, v86, v87
	v_cvt_pk_bf16_f32 v200, v88, v89
	v_cvt_pk_bf16_f32 v201, v90, v91
	v_sub_f32_e32 v0, v92, v168
	v_sub_f32_e32 v1, v93, v168
	v_sub_f32_e32 v2, v94, v168
	v_sub_f32_e32 v3, v95, v168
	v_mul_f32_e32 v0, 0x3d800000, v0
	v_mul_f32_e32 v1, 0x3d800000, v1
	v_mul_f32_e32 v2, 0x3d800000, v2
	v_mul_f32_e32 v3, 0x3d800000, v3
	v_mul_f32_e32 v0, 0x3fb8aa3b, v0
	v_mul_f32_e32 v1, 0x3fb8aa3b, v1
	v_mul_f32_e32 v2, 0x3fb8aa3b, v2
	v_mul_f32_e32 v3, 0x3fb8aa3b, v3
	v_exp_f32_e32 v92, v0
	v_exp_f32_e32 v93, v1
	v_exp_f32_e32 v94, v2
	v_exp_f32_e32 v95, v3
	v_add_f32_e32 v221, v92, v221
	v_add_f32_e32 v221, v93, v221
	v_add_f32_e32 v221, v94, v221
	v_add_f32_e32 v221, v95, v221
	v_sub_f32_e32 v0, v96, v168
	v_sub_f32_e32 v1, v97, v168
	v_sub_f32_e32 v2, v98, v168
	v_sub_f32_e32 v3, v99, v168
	v_mul_f32_e32 v0, 0x3d800000, v0
	v_mul_f32_e32 v1, 0x3d800000, v1
	v_mul_f32_e32 v2, 0x3d800000, v2
	v_mul_f32_e32 v3, 0x3d800000, v3
	v_mul_f32_e32 v0, 0x3fb8aa3b, v0
	v_mul_f32_e32 v1, 0x3fb8aa3b, v1
	v_mul_f32_e32 v2, 0x3fb8aa3b, v2
	v_mul_f32_e32 v3, 0x3fb8aa3b, v3
	v_exp_f32_e32 v96, v0
	v_exp_f32_e32 v97, v1
	v_exp_f32_e32 v98, v2
	v_exp_f32_e32 v99, v3
	v_add_f32_e32 v221, v96, v221
	v_add_f32_e32 v221, v97, v221
	v_add_f32_e32 v221, v98, v221
	v_add_f32_e32 v221, v99, v221
	v_cvt_pk_bf16_f32 v202, v92, v93
	v_cvt_pk_bf16_f32 v203, v94, v95
	v_cvt_pk_bf16_f32 v204, v96, v97
	v_cvt_pk_bf16_f32 v205, v98, v99
	v_sub_f32_e32 v0, v100, v168
	v_sub_f32_e32 v1, v101, v168
	v_sub_f32_e32 v2, v102, v168
	v_sub_f32_e32 v3, v103, v168
	v_mul_f32_e32 v0, 0x3d800000, v0
	v_mul_f32_e32 v1, 0x3d800000, v1
	v_mul_f32_e32 v2, 0x3d800000, v2
	v_mul_f32_e32 v3, 0x3d800000, v3
	v_mul_f32_e32 v0, 0x3fb8aa3b, v0
	v_mul_f32_e32 v1, 0x3fb8aa3b, v1
	v_mul_f32_e32 v2, 0x3fb8aa3b, v2
	v_mul_f32_e32 v3, 0x3fb8aa3b, v3
	v_exp_f32_e32 v100, v0
	v_exp_f32_e32 v101, v1
	v_exp_f32_e32 v102, v2
	v_exp_f32_e32 v103, v3
	v_add_f32_e32 v221, v100, v221
	v_add_f32_e32 v221, v101, v221
	v_add_f32_e32 v221, v102, v221
	v_add_f32_e32 v221, v103, v221
	v_sub_f32_e32 v0, v104, v168
	v_sub_f32_e32 v1, v105, v168
	v_sub_f32_e32 v2, v106, v168
	v_sub_f32_e32 v3, v107, v168
	v_mul_f32_e32 v0, 0x3d800000, v0
	v_mul_f32_e32 v1, 0x3d800000, v1
	v_mul_f32_e32 v2, 0x3d800000, v2
	v_mul_f32_e32 v3, 0x3d800000, v3
	v_mul_f32_e32 v0, 0x3fb8aa3b, v0
	v_mul_f32_e32 v1, 0x3fb8aa3b, v1
	v_mul_f32_e32 v2, 0x3fb8aa3b, v2
	v_mul_f32_e32 v3, 0x3fb8aa3b, v3
	v_exp_f32_e32 v104, v0
	v_exp_f32_e32 v105, v1
	v_exp_f32_e32 v106, v2
	v_exp_f32_e32 v107, v3
	v_add_f32_e32 v221, v104, v221
	v_add_f32_e32 v221, v105, v221
	v_add_f32_e32 v221, v106, v221
	v_add_f32_e32 v221, v107, v221
	v_cvt_pk_bf16_f32 v206, v100, v101
	v_cvt_pk_bf16_f32 v207, v102, v103
	v_cvt_pk_bf16_f32 v208, v104, v105
	v_cvt_pk_bf16_f32 v209, v106, v107
	v_sub_f32_e32 v0, v108, v168
	v_sub_f32_e32 v1, v109, v168
	v_sub_f32_e32 v2, v110, v168
	v_sub_f32_e32 v3, v111, v168
	v_mul_f32_e32 v0, 0x3d800000, v0
	v_mul_f32_e32 v1, 0x3d800000, v1
	v_mul_f32_e32 v2, 0x3d800000, v2
	v_mul_f32_e32 v3, 0x3d800000, v3
	v_mul_f32_e32 v0, 0x3fb8aa3b, v0
	v_mul_f32_e32 v1, 0x3fb8aa3b, v1
	v_mul_f32_e32 v2, 0x3fb8aa3b, v2
	v_mul_f32_e32 v3, 0x3fb8aa3b, v3
	v_exp_f32_e32 v108, v0
	v_exp_f32_e32 v109, v1
	v_exp_f32_e32 v110, v2
	v_exp_f32_e32 v111, v3
	v_add_f32_e32 v221, v108, v221
	v_add_f32_e32 v221, v109, v221
	v_add_f32_e32 v221, v110, v221
	v_add_f32_e32 v221, v111, v221
	v_sub_f32_e32 v0, v112, v168
	v_sub_f32_e32 v1, v113, v168
	v_sub_f32_e32 v2, v114, v168
	v_sub_f32_e32 v3, v115, v168
	v_mul_f32_e32 v0, 0x3d800000, v0
	v_mul_f32_e32 v1, 0x3d800000, v1
	v_mul_f32_e32 v2, 0x3d800000, v2
	v_mul_f32_e32 v3, 0x3d800000, v3
	v_mul_f32_e32 v0, 0x3fb8aa3b, v0
	v_mul_f32_e32 v1, 0x3fb8aa3b, v1
	v_mul_f32_e32 v2, 0x3fb8aa3b, v2
	v_mul_f32_e32 v3, 0x3fb8aa3b, v3
	v_exp_f32_e32 v112, v0
	v_exp_f32_e32 v113, v1
	v_exp_f32_e32 v114, v2
	v_exp_f32_e32 v115, v3
	v_add_f32_e32 v221, v112, v221
	v_add_f32_e32 v221, v113, v221
	v_add_f32_e32 v221, v114, v221
	v_add_f32_e32 v221, v115, v221
	v_cvt_pk_bf16_f32 v224, v108, v109
	v_cvt_pk_bf16_f32 v225, v110, v111
	v_cvt_pk_bf16_f32 v226, v112, v113
	v_cvt_pk_bf16_f32 v227, v114, v115
	v_sub_f32_e32 v0, v116, v168
	v_sub_f32_e32 v1, v117, v168
	v_sub_f32_e32 v2, v118, v168
	v_sub_f32_e32 v3, v119, v168
	v_mul_f32_e32 v0, 0x3d800000, v0
	v_mul_f32_e32 v1, 0x3d800000, v1
	v_mul_f32_e32 v2, 0x3d800000, v2
	v_mul_f32_e32 v3, 0x3d800000, v3
	v_mul_f32_e32 v0, 0x3fb8aa3b, v0
	v_mul_f32_e32 v1, 0x3fb8aa3b, v1
	v_mul_f32_e32 v2, 0x3fb8aa3b, v2
	v_mul_f32_e32 v3, 0x3fb8aa3b, v3
	v_exp_f32_e32 v116, v0
	v_exp_f32_e32 v117, v1
	v_exp_f32_e32 v118, v2
	v_exp_f32_e32 v119, v3
	v_add_f32_e32 v221, v116, v221
	v_add_f32_e32 v221, v117, v221
	v_add_f32_e32 v221, v118, v221
	v_add_f32_e32 v221, v119, v221
	v_sub_f32_e32 v0, v120, v168
	v_sub_f32_e32 v1, v121, v168
	v_sub_f32_e32 v2, v122, v168
	v_sub_f32_e32 v3, v123, v168
	v_mul_f32_e32 v0, 0x3d800000, v0
	v_mul_f32_e32 v1, 0x3d800000, v1
	v_mul_f32_e32 v2, 0x3d800000, v2
	v_mul_f32_e32 v3, 0x3d800000, v3
	v_mul_f32_e32 v0, 0x3fb8aa3b, v0
	v_mul_f32_e32 v1, 0x3fb8aa3b, v1
	v_mul_f32_e32 v2, 0x3fb8aa3b, v2
	v_mul_f32_e32 v3, 0x3fb8aa3b, v3
	v_exp_f32_e32 v120, v0
	v_exp_f32_e32 v121, v1
	v_exp_f32_e32 v122, v2
	v_exp_f32_e32 v123, v3
	v_add_f32_e32 v221, v120, v221
	v_add_f32_e32 v221, v121, v221
	v_add_f32_e32 v221, v122, v221
	v_add_f32_e32 v221, v123, v221
	v_cvt_pk_bf16_f32 v228, v116, v117
	v_cvt_pk_bf16_f32 v229, v118, v119
	v_cvt_pk_bf16_f32 v230, v120, v121
	v_cvt_pk_bf16_f32 v231, v122, v123
	v_sub_f32_e32 v0, v124, v168
	v_sub_f32_e32 v1, v125, v168
	v_sub_f32_e32 v2, v126, v168
	v_sub_f32_e32 v3, v127, v168
	v_mul_f32_e32 v0, 0x3d800000, v0
	v_mul_f32_e32 v1, 0x3d800000, v1
	v_mul_f32_e32 v2, 0x3d800000, v2
	v_mul_f32_e32 v3, 0x3d800000, v3
	v_mul_f32_e32 v0, 0x3fb8aa3b, v0
	v_mul_f32_e32 v1, 0x3fb8aa3b, v1
	v_mul_f32_e32 v2, 0x3fb8aa3b, v2
	v_mul_f32_e32 v3, 0x3fb8aa3b, v3
	v_exp_f32_e32 v124, v0
	v_exp_f32_e32 v125, v1
	v_exp_f32_e32 v126, v2
	v_exp_f32_e32 v127, v3
	v_add_f32_e32 v221, v124, v221
	v_add_f32_e32 v221, v125, v221
	v_add_f32_e32 v221, v126, v221
	v_add_f32_e32 v221, v127, v221
	v_sub_f32_e32 v0, v128, v168
	v_sub_f32_e32 v1, v129, v168
	v_sub_f32_e32 v2, v130, v168
	v_sub_f32_e32 v3, v131, v168
	v_mul_f32_e32 v0, 0x3d800000, v0
	v_mul_f32_e32 v1, 0x3d800000, v1
	v_mul_f32_e32 v2, 0x3d800000, v2
	v_mul_f32_e32 v3, 0x3d800000, v3
	v_mul_f32_e32 v0, 0x3fb8aa3b, v0
	v_mul_f32_e32 v1, 0x3fb8aa3b, v1
	v_mul_f32_e32 v2, 0x3fb8aa3b, v2
	v_mul_f32_e32 v3, 0x3fb8aa3b, v3
	v_exp_f32_e32 v128, v0
	v_exp_f32_e32 v129, v1
	v_exp_f32_e32 v130, v2
	v_exp_f32_e32 v131, v3
	v_add_f32_e32 v221, v128, v221
	v_add_f32_e32 v221, v129, v221
	v_add_f32_e32 v221, v130, v221
	v_add_f32_e32 v221, v131, v221
	v_cvt_pk_bf16_f32 v232, v124, v125
	v_cvt_pk_bf16_f32 v233, v126, v127
	v_cvt_pk_bf16_f32 v234, v128, v129
	v_cvt_pk_bf16_f32 v235, v130, v131
	ds_bpermute_b32 v169, v189, v221
	s_waitcnt lgkmcnt(0)
	v_add_f32_e32 v221, v221, v169
	ds_bpermute_b32 v169, v222, v221
	s_waitcnt lgkmcnt(0)
	v_add_f32_e32 v221, v221, v169
	s_waitcnt vmcnt(0)
	ds_write_b128 v187, v[236:239]
	ds_write_b128 v187, v[240:243] offset:128
	ds_write_b128 v187, v[164:167] offset:256
	ds_write_b128 v187, v[182:185] offset:384
	v_add_co_u32_e32 v218, vcc, 0x80000, v210
	s_nop 1
	v_addc_co_u32_e32 v219, vcc, 0, v211, vcc
	global_load_dwordx4 v[236:239], v[218:219], off offset:2048
	global_load_dwordx4 v[240:243], v[218:219], off offset:2176
	global_load_dwordx4 v[164:167], v[218:219], off offset:2304
	global_load_dwordx4 v[182:185], v[218:219], off offset:2432
	s_waitcnt lgkmcnt(0)
	s_barrier
	ds_read_b64_tr_b16 v[0:1], v180
	ds_read_b64_tr_b16 v[2:3], v180 offset:8448
	ds_read_b64_tr_b16 v[168:169], v180 offset:16896
	ds_read_b64_tr_b16 v[170:171], v180 offset:25344
	ds_read_b64_tr_b16 v[172:173], v180 offset:32
	ds_read_b64_tr_b16 v[174:175], v180 offset:8480
	ds_read_b64_tr_b16 v[176:177], v180 offset:16928
	ds_read_b64_tr_b16 v[178:179], v180 offset:25376
	s_waitcnt lgkmcnt(4)
	v_mfma_f32_16x16x32_bf16 v[4:7], v[0:3], v[132:135], 0
	v_mfma_f32_16x16x32_bf16 v[68:71], v[0:3], v[190:193], 0
	v_mfma_f32_16x16x32_bf16 v[4:7], v[168:171], v[136:139], v[4:7]
	v_mfma_f32_16x16x32_bf16 v[68:71], v[168:171], v[194:197], v[68:71]
	ds_read_b64_tr_b16 v[0:1], v180 offset:64
	ds_read_b64_tr_b16 v[2:3], v180 offset:8512
	ds_read_b64_tr_b16 v[168:169], v180 offset:16960
	ds_read_b64_tr_b16 v[170:171], v180 offset:25408
	s_waitcnt lgkmcnt(4)
	v_mfma_f32_16x16x32_bf16 v[8:11], v[172:175], v[132:135], 0
	v_mfma_f32_16x16x32_bf16 v[72:75], v[172:175], v[190:193], 0
	v_mfma_f32_16x16x32_bf16 v[8:11], v[176:179], v[136:139], v[8:11]
	v_mfma_f32_16x16x32_bf16 v[72:75], v[176:179], v[194:197], v[72:75]
	ds_read_b64_tr_b16 v[172:173], v180 offset:96
	ds_read_b64_tr_b16 v[174:175], v180 offset:8544
	ds_read_b64_tr_b16 v[176:177], v180 offset:16992
	ds_read_b64_tr_b16 v[178:179], v180 offset:25440
	s_waitcnt lgkmcnt(4)
	v_mfma_f32_16x16x32_bf16 v[12:15], v[0:3], v[132:135], 0
	v_mfma_f32_16x16x32_bf16 v[76:79], v[0:3], v[190:193], 0
	v_mfma_f32_16x16x32_bf16 v[12:15], v[168:171], v[136:139], v[12:15]
	v_mfma_f32_16x16x32_bf16 v[76:79], v[168:171], v[194:197], v[76:79]
	ds_read_b64_tr_b16 v[0:1], v180 offset:128
	ds_read_b64_tr_b16 v[2:3], v180 offset:8576
	ds_read_b64_tr_b16 v[168:169], v180 offset:17024
	ds_read_b64_tr_b16 v[170:171], v180 offset:25472
	s_waitcnt lgkmcnt(4)
	v_mfma_f32_16x16x32_bf16 v[16:19], v[172:175], v[132:135], 0
	v_mfma_f32_16x16x32_bf16 v[80:83], v[172:175], v[190:193], 0
	v_mfma_f32_16x16x32_bf16 v[16:19], v[176:179], v[136:139], v[16:19]
	v_mfma_f32_16x16x32_bf16 v[80:83], v[176:179], v[194:197], v[80:83]
	ds_read_b64_tr_b16 v[172:173], v180 offset:160
	ds_read_b64_tr_b16 v[174:175], v180 offset:8608
	ds_read_b64_tr_b16 v[176:177], v180 offset:17056
	ds_read_b64_tr_b16 v[178:179], v180 offset:25504
	s_waitcnt lgkmcnt(4)
	v_mfma_f32_16x16x32_bf16 v[20:23], v[0:3], v[132:135], 0
	v_mfma_f32_16x16x32_bf16 v[84:87], v[0:3], v[190:193], 0
	v_mfma_f32_16x16x32_bf16 v[20:23], v[168:171], v[136:139], v[20:23]
	v_mfma_f32_16x16x32_bf16 v[84:87], v[168:171], v[194:197], v[84:87]
	ds_read_b64_tr_b16 v[0:1], v180 offset:192
	ds_read_b64_tr_b16 v[2:3], v180 offset:8640
	ds_read_b64_tr_b16 v[168:169], v180 offset:17088
	ds_read_b64_tr_b16 v[170:171], v180 offset:25536
	s_waitcnt lgkmcnt(4)
	v_mfma_f32_16x16x32_bf16 v[24:27], v[172:175], v[132:135], 0
	v_mfma_f32_16x16x32_bf16 v[88:91], v[172:175], v[190:193], 0
	v_mfma_f32_16x16x32_bf16 v[24:27], v[176:179], v[136:139], v[24:27]
	v_mfma_f32_16x16x32_bf16 v[88:91], v[176:179], v[194:197], v[88:91]
	ds_read_b64_tr_b16 v[172:173], v180 offset:224
	ds_read_b64_tr_b16 v[174:175], v180 offset:8672
	ds_read_b64_tr_b16 v[176:177], v180 offset:17120
	ds_read_b64_tr_b16 v[178:179], v180 offset:25568
	s_waitcnt lgkmcnt(4)
	v_mfma_f32_16x16x32_bf16 v[28:31], v[0:3], v[132:135], 0
	v_mfma_f32_16x16x32_bf16 v[92:95], v[0:3], v[190:193], 0
	v_mfma_f32_16x16x32_bf16 v[28:31], v[168:171], v[136:139], v[28:31]
	v_mfma_f32_16x16x32_bf16 v[92:95], v[168:171], v[194:197], v[92:95]
	ds_read_b64_tr_b16 v[0:1], v180 offset:256
	ds_read_b64_tr_b16 v[2:3], v180 offset:8704
	ds_read_b64_tr_b16 v[168:169], v180 offset:17152
	ds_read_b64_tr_b16 v[170:171], v180 offset:25600
	s_waitcnt lgkmcnt(4)
	v_mfma_f32_16x16x32_bf16 v[32:35], v[172:175], v[132:135], 0
	v_mfma_f32_16x16x32_bf16 v[96:99], v[172:175], v[190:193], 0
	v_mfma_f32_16x16x32_bf16 v[32:35], v[176:179], v[136:139], v[32:35]
	v_mfma_f32_16x16x32_bf16 v[96:99], v[176:179], v[194:197], v[96:99]
	ds_read_b64_tr_b16 v[172:173], v180 offset:288
	ds_read_b64_tr_b16 v[174:175], v180 offset:8736
	ds_read_b64_tr_b16 v[176:177], v180 offset:17184
	ds_read_b64_tr_b16 v[178:179], v180 offset:25632
	s_waitcnt lgkmcnt(4)
	v_mfma_f32_16x16x32_bf16 v[36:39], v[0:3], v[132:135], 0
	v_mfma_f32_16x16x32_bf16 v[100:103], v[0:3], v[190:193], 0
	v_mfma_f32_16x16x32_bf16 v[36:39], v[168:171], v[136:139], v[36:39]
	v_mfma_f32_16x16x32_bf16 v[100:103], v[168:171], v[194:197], v[100:103]
	ds_read_b64_tr_b16 v[0:1], v180 offset:320
	ds_read_b64_tr_b16 v[2:3], v180 offset:8768
	ds_read_b64_tr_b16 v[168:169], v180 offset:17216
	ds_read_b64_tr_b16 v[170:171], v180 offset:25664
	s_waitcnt lgkmcnt(4)
	v_mfma_f32_16x16x32_bf16 v[40:43], v[172:175], v[132:135], 0
	v_mfma_f32_16x16x32_bf16 v[104:107], v[172:175], v[190:193], 0
	v_mfma_f32_16x16x32_bf16 v[40:43], v[176:179], v[136:139], v[40:43]
	v_mfma_f32_16x16x32_bf16 v[104:107], v[176:179], v[194:197], v[104:107]
	ds_read_b64_tr_b16 v[172:173], v180 offset:352
	ds_read_b64_tr_b16 v[174:175], v180 offset:8800
	ds_read_b64_tr_b16 v[176:177], v180 offset:17248
	ds_read_b64_tr_b16 v[178:179], v180 offset:25696
	s_waitcnt lgkmcnt(4)
	v_mfma_f32_16x16x32_bf16 v[44:47], v[0:3], v[132:135], 0
	v_mfma_f32_16x16x32_bf16 v[108:111], v[0:3], v[190:193], 0
	v_mfma_f32_16x16x32_bf16 v[44:47], v[168:171], v[136:139], v[44:47]
	v_mfma_f32_16x16x32_bf16 v[108:111], v[168:171], v[194:197], v[108:111]
	ds_read_b64_tr_b16 v[0:1], v180 offset:384
	ds_read_b64_tr_b16 v[2:3], v180 offset:8832
	ds_read_b64_tr_b16 v[168:169], v180 offset:17280
	ds_read_b64_tr_b16 v[170:171], v180 offset:25728
	s_waitcnt lgkmcnt(4)
	v_mfma_f32_16x16x32_bf16 v[48:51], v[172:175], v[132:135], 0
	v_mfma_f32_16x16x32_bf16 v[112:115], v[172:175], v[190:193], 0
	v_mfma_f32_16x16x32_bf16 v[48:51], v[176:179], v[136:139], v[48:51]
	v_mfma_f32_16x16x32_bf16 v[112:115], v[176:179], v[194:197], v[112:115]
	ds_read_b64_tr_b16 v[172:173], v180 offset:416
	ds_read_b64_tr_b16 v[174:175], v180 offset:8864
	ds_read_b64_tr_b16 v[176:177], v180 offset:17312
	ds_read_b64_tr_b16 v[178:179], v180 offset:25760
	s_waitcnt lgkmcnt(4)
	v_mfma_f32_16x16x32_bf16 v[52:55], v[0:3], v[132:135], 0
	v_mfma_f32_16x16x32_bf16 v[116:119], v[0:3], v[190:193], 0
	v_mfma_f32_16x16x32_bf16 v[52:55], v[168:171], v[136:139], v[52:55]
	v_mfma_f32_16x16x32_bf16 v[116:119], v[168:171], v[194:197], v[116:119]
	ds_read_b64_tr_b16 v[0:1], v180 offset:448
	ds_read_b64_tr_b16 v[2:3], v180 offset:8896
	ds_read_b64_tr_b16 v[168:169], v180 offset:17344
	ds_read_b64_tr_b16 v[170:171], v180 offset:25792
	s_waitcnt lgkmcnt(4)
	v_mfma_f32_16x16x32_bf16 v[56:59], v[172:175], v[132:135], 0
	v_mfma_f32_16x16x32_bf16 v[120:123], v[172:175], v[190:193], 0
	v_mfma_f32_16x16x32_bf16 v[56:59], v[176:179], v[136:139], v[56:59]
	v_mfma_f32_16x16x32_bf16 v[120:123], v[176:179], v[194:197], v[120:123]
	ds_read_b64_tr_b16 v[172:173], v180 offset:480
	ds_read_b64_tr_b16 v[174:175], v180 offset:8928
	ds_read_b64_tr_b16 v[176:177], v180 offset:17376
	ds_read_b64_tr_b16 v[178:179], v180 offset:25824
	s_waitcnt lgkmcnt(4)
	v_mfma_f32_16x16x32_bf16 v[60:63], v[0:3], v[132:135], 0
	v_mfma_f32_16x16x32_bf16 v[124:127], v[0:3], v[190:193], 0
	v_mfma_f32_16x16x32_bf16 v[60:63], v[168:171], v[136:139], v[60:63]
	v_mfma_f32_16x16x32_bf16 v[124:127], v[168:171], v[194:197], v[124:127]
	s_waitcnt lgkmcnt(0)
	v_mfma_f32_16x16x32_bf16 v[64:67], v[172:175], v[132:135], 0
	v_mfma_f32_16x16x32_bf16 v[128:131], v[172:175], v[190:193], 0
	v_mfma_f32_16x16x32_bf16 v[64:67], v[176:179], v[136:139], v[64:67]
	v_mfma_f32_16x16x32_bf16 v[128:131], v[176:179], v[194:197], v[128:131]
	s_waitcnt vmcnt(0)
	ds_write_b128 v187, v[236:239] offset:33792
	ds_write_b128 v187, v[240:243] offset:33920
	ds_write_b128 v187, v[164:167] offset:34048
	ds_write_b128 v187, v[182:185] offset:34176
	v_add_co_u32_e32 v218, vcc, 0x100000, v210
	s_nop 1
	v_addc_co_u32_e32 v219, vcc, 0, v211, vcc
	global_load_dwordx4 v[236:239], v[218:219], off offset:2048
	global_load_dwordx4 v[240:243], v[218:219], off offset:2176
	global_load_dwordx4 v[164:167], v[218:219], off offset:2304
	global_load_dwordx4 v[182:185], v[218:219], off offset:2432
	s_waitcnt lgkmcnt(0)
	s_barrier
	ds_read_b64_tr_b16 v[0:1], v180 offset:33792
	ds_read_b64_tr_b16 v[2:3], v180 offset:42240
	ds_read_b64_tr_b16 v[168:169], v180 offset:50688
	ds_read_b64_tr_b16 v[170:171], v180 offset:59136
	ds_read_b64_tr_b16 v[172:173], v180 offset:33824
	ds_read_b64_tr_b16 v[174:175], v180 offset:42272
	ds_read_b64_tr_b16 v[176:177], v180 offset:50720
	ds_read_b64_tr_b16 v[178:179], v180 offset:59168
	s_waitcnt lgkmcnt(4)
	v_mfma_f32_16x16x32_bf16 v[4:7], v[0:3], v[140:143], v[4:7]
	v_mfma_f32_16x16x32_bf16 v[68:71], v[0:3], v[198:201], v[68:71]
	v_mfma_f32_16x16x32_bf16 v[4:7], v[168:171], v[144:147], v[4:7]
	v_mfma_f32_16x16x32_bf16 v[68:71], v[168:171], v[202:205], v[68:71]
	ds_read_b64_tr_b16 v[0:1], v180 offset:33856
	ds_read_b64_tr_b16 v[2:3], v180 offset:42304
	ds_read_b64_tr_b16 v[168:169], v180 offset:50752
	ds_read_b64_tr_b16 v[170:171], v180 offset:59200
	s_waitcnt lgkmcnt(4)
	v_mfma_f32_16x16x32_bf16 v[8:11], v[172:175], v[140:143], v[8:11]
	v_mfma_f32_16x16x32_bf16 v[72:75], v[172:175], v[198:201], v[72:75]
	v_mfma_f32_16x16x32_bf16 v[8:11], v[176:179], v[144:147], v[8:11]
	v_mfma_f32_16x16x32_bf16 v[72:75], v[176:179], v[202:205], v[72:75]
	ds_read_b64_tr_b16 v[172:173], v180 offset:33888
	ds_read_b64_tr_b16 v[174:175], v180 offset:42336
	ds_read_b64_tr_b16 v[176:177], v180 offset:50784
	ds_read_b64_tr_b16 v[178:179], v180 offset:59232
	s_waitcnt lgkmcnt(4)
	v_mfma_f32_16x16x32_bf16 v[12:15], v[0:3], v[140:143], v[12:15]
	v_mfma_f32_16x16x32_bf16 v[76:79], v[0:3], v[198:201], v[76:79]
	v_mfma_f32_16x16x32_bf16 v[12:15], v[168:171], v[144:147], v[12:15]
	v_mfma_f32_16x16x32_bf16 v[76:79], v[168:171], v[202:205], v[76:79]
	ds_read_b64_tr_b16 v[0:1], v180 offset:33920
	ds_read_b64_tr_b16 v[2:3], v180 offset:42368
	ds_read_b64_tr_b16 v[168:169], v180 offset:50816
	ds_read_b64_tr_b16 v[170:171], v180 offset:59264
	s_waitcnt lgkmcnt(4)
	v_mfma_f32_16x16x32_bf16 v[16:19], v[172:175], v[140:143], v[16:19]
	v_mfma_f32_16x16x32_bf16 v[80:83], v[172:175], v[198:201], v[80:83]
	v_mfma_f32_16x16x32_bf16 v[16:19], v[176:179], v[144:147], v[16:19]
	v_mfma_f32_16x16x32_bf16 v[80:83], v[176:179], v[202:205], v[80:83]
	ds_read_b64_tr_b16 v[172:173], v180 offset:33952
	ds_read_b64_tr_b16 v[174:175], v180 offset:42400
	ds_read_b64_tr_b16 v[176:177], v180 offset:50848
	ds_read_b64_tr_b16 v[178:179], v180 offset:59296
	s_waitcnt lgkmcnt(4)
	v_mfma_f32_16x16x32_bf16 v[20:23], v[0:3], v[140:143], v[20:23]
	v_mfma_f32_16x16x32_bf16 v[84:87], v[0:3], v[198:201], v[84:87]
	v_mfma_f32_16x16x32_bf16 v[20:23], v[168:171], v[144:147], v[20:23]
	v_mfma_f32_16x16x32_bf16 v[84:87], v[168:171], v[202:205], v[84:87]
	ds_read_b64_tr_b16 v[0:1], v180 offset:33984
	ds_read_b64_tr_b16 v[2:3], v180 offset:42432
	ds_read_b64_tr_b16 v[168:169], v180 offset:50880
	ds_read_b64_tr_b16 v[170:171], v180 offset:59328
	s_waitcnt lgkmcnt(4)
	v_mfma_f32_16x16x32_bf16 v[24:27], v[172:175], v[140:143], v[24:27]
	v_mfma_f32_16x16x32_bf16 v[88:91], v[172:175], v[198:201], v[88:91]
	v_mfma_f32_16x16x32_bf16 v[24:27], v[176:179], v[144:147], v[24:27]
	v_mfma_f32_16x16x32_bf16 v[88:91], v[176:179], v[202:205], v[88:91]
	ds_read_b64_tr_b16 v[172:173], v180 offset:34016
	ds_read_b64_tr_b16 v[174:175], v180 offset:42464
	ds_read_b64_tr_b16 v[176:177], v180 offset:50912
	ds_read_b64_tr_b16 v[178:179], v180 offset:59360
	s_waitcnt lgkmcnt(4)
	v_mfma_f32_16x16x32_bf16 v[28:31], v[0:3], v[140:143], v[28:31]
	v_mfma_f32_16x16x32_bf16 v[92:95], v[0:3], v[198:201], v[92:95]
	v_mfma_f32_16x16x32_bf16 v[28:31], v[168:171], v[144:147], v[28:31]
	v_mfma_f32_16x16x32_bf16 v[92:95], v[168:171], v[202:205], v[92:95]
	ds_read_b64_tr_b16 v[0:1], v180 offset:34048
	ds_read_b64_tr_b16 v[2:3], v180 offset:42496
	ds_read_b64_tr_b16 v[168:169], v180 offset:50944
	ds_read_b64_tr_b16 v[170:171], v180 offset:59392
	s_waitcnt lgkmcnt(4)
	v_mfma_f32_16x16x32_bf16 v[32:35], v[172:175], v[140:143], v[32:35]
	v_mfma_f32_16x16x32_bf16 v[96:99], v[172:175], v[198:201], v[96:99]
	v_mfma_f32_16x16x32_bf16 v[32:35], v[176:179], v[144:147], v[32:35]
	v_mfma_f32_16x16x32_bf16 v[96:99], v[176:179], v[202:205], v[96:99]
	ds_read_b64_tr_b16 v[172:173], v180 offset:34080
	ds_read_b64_tr_b16 v[174:175], v180 offset:42528
	ds_read_b64_tr_b16 v[176:177], v180 offset:50976
	ds_read_b64_tr_b16 v[178:179], v180 offset:59424
	s_waitcnt lgkmcnt(4)
	v_mfma_f32_16x16x32_bf16 v[36:39], v[0:3], v[140:143], v[36:39]
	v_mfma_f32_16x16x32_bf16 v[100:103], v[0:3], v[198:201], v[100:103]
	v_mfma_f32_16x16x32_bf16 v[36:39], v[168:171], v[144:147], v[36:39]
	v_mfma_f32_16x16x32_bf16 v[100:103], v[168:171], v[202:205], v[100:103]
	ds_read_b64_tr_b16 v[0:1], v180 offset:34112
	ds_read_b64_tr_b16 v[2:3], v180 offset:42560
	ds_read_b64_tr_b16 v[168:169], v180 offset:51008
	ds_read_b64_tr_b16 v[170:171], v180 offset:59456
	s_waitcnt lgkmcnt(4)
	v_mfma_f32_16x16x32_bf16 v[40:43], v[172:175], v[140:143], v[40:43]
	v_mfma_f32_16x16x32_bf16 v[104:107], v[172:175], v[198:201], v[104:107]
	v_mfma_f32_16x16x32_bf16 v[40:43], v[176:179], v[144:147], v[40:43]
	v_mfma_f32_16x16x32_bf16 v[104:107], v[176:179], v[202:205], v[104:107]
	ds_read_b64_tr_b16 v[172:173], v180 offset:34144
	ds_read_b64_tr_b16 v[174:175], v180 offset:42592
	ds_read_b64_tr_b16 v[176:177], v180 offset:51040
	ds_read_b64_tr_b16 v[178:179], v180 offset:59488
	s_waitcnt lgkmcnt(4)
	v_mfma_f32_16x16x32_bf16 v[44:47], v[0:3], v[140:143], v[44:47]
	v_mfma_f32_16x16x32_bf16 v[108:111], v[0:3], v[198:201], v[108:111]
	v_mfma_f32_16x16x32_bf16 v[44:47], v[168:171], v[144:147], v[44:47]
	v_mfma_f32_16x16x32_bf16 v[108:111], v[168:171], v[202:205], v[108:111]
	ds_read_b64_tr_b16 v[0:1], v180 offset:34176
	ds_read_b64_tr_b16 v[2:3], v180 offset:42624
	ds_read_b64_tr_b16 v[168:169], v180 offset:51072
	ds_read_b64_tr_b16 v[170:171], v180 offset:59520
	s_waitcnt lgkmcnt(4)
	v_mfma_f32_16x16x32_bf16 v[48:51], v[172:175], v[140:143], v[48:51]
	v_mfma_f32_16x16x32_bf16 v[112:115], v[172:175], v[198:201], v[112:115]
	v_mfma_f32_16x16x32_bf16 v[48:51], v[176:179], v[144:147], v[48:51]
	v_mfma_f32_16x16x32_bf16 v[112:115], v[176:179], v[202:205], v[112:115]
	ds_read_b64_tr_b16 v[172:173], v180 offset:34208
	ds_read_b64_tr_b16 v[174:175], v180 offset:42656
	ds_read_b64_tr_b16 v[176:177], v180 offset:51104
	ds_read_b64_tr_b16 v[178:179], v180 offset:59552
	s_waitcnt lgkmcnt(4)
	v_mfma_f32_16x16x32_bf16 v[52:55], v[0:3], v[140:143], v[52:55]
	v_mfma_f32_16x16x32_bf16 v[116:119], v[0:3], v[198:201], v[116:119]
	v_mfma_f32_16x16x32_bf16 v[52:55], v[168:171], v[144:147], v[52:55]
	v_mfma_f32_16x16x32_bf16 v[116:119], v[168:171], v[202:205], v[116:119]
	ds_read_b64_tr_b16 v[0:1], v180 offset:34240
	ds_read_b64_tr_b16 v[2:3], v180 offset:42688
	ds_read_b64_tr_b16 v[168:169], v180 offset:51136
	ds_read_b64_tr_b16 v[170:171], v180 offset:59584
	s_waitcnt lgkmcnt(4)
	v_mfma_f32_16x16x32_bf16 v[56:59], v[172:175], v[140:143], v[56:59]
	v_mfma_f32_16x16x32_bf16 v[120:123], v[172:175], v[198:201], v[120:123]
	v_mfma_f32_16x16x32_bf16 v[56:59], v[176:179], v[144:147], v[56:59]
	v_mfma_f32_16x16x32_bf16 v[120:123], v[176:179], v[202:205], v[120:123]
	ds_read_b64_tr_b16 v[172:173], v180 offset:34272
	ds_read_b64_tr_b16 v[174:175], v180 offset:42720
	ds_read_b64_tr_b16 v[176:177], v180 offset:51168
	ds_read_b64_tr_b16 v[178:179], v180 offset:59616
	s_waitcnt lgkmcnt(4)
	v_mfma_f32_16x16x32_bf16 v[60:63], v[0:3], v[140:143], v[60:63]
	v_mfma_f32_16x16x32_bf16 v[124:127], v[0:3], v[198:201], v[124:127]
	v_mfma_f32_16x16x32_bf16 v[60:63], v[168:171], v[144:147], v[60:63]
	v_mfma_f32_16x16x32_bf16 v[124:127], v[168:171], v[202:205], v[124:127]
	s_waitcnt lgkmcnt(0)
	v_mfma_f32_16x16x32_bf16 v[64:67], v[172:175], v[140:143], v[64:67]
	v_mfma_f32_16x16x32_bf16 v[128:131], v[172:175], v[198:201], v[128:131]
	v_mfma_f32_16x16x32_bf16 v[64:67], v[176:179], v[144:147], v[64:67]
	v_mfma_f32_16x16x32_bf16 v[128:131], v[176:179], v[202:205], v[128:131]
	s_waitcnt vmcnt(0)
	ds_write_b128 v187, v[236:239]
	ds_write_b128 v187, v[240:243] offset:128
	ds_write_b128 v187, v[164:167] offset:256
	ds_write_b128 v187, v[182:185] offset:384
	v_add_co_u32_e32 v218, vcc, 0x180000, v210
	s_nop 1
	v_addc_co_u32_e32 v219, vcc, 0, v211, vcc
	global_load_dwordx4 v[236:239], v[218:219], off offset:2048
	global_load_dwordx4 v[240:243], v[218:219], off offset:2176
	global_load_dwordx4 v[164:167], v[218:219], off offset:2304
	global_load_dwordx4 v[182:185], v[218:219], off offset:2432
	s_waitcnt lgkmcnt(0)
	s_barrier
	ds_read_b64_tr_b16 v[0:1], v180
	ds_read_b64_tr_b16 v[2:3], v180 offset:8448
	ds_read_b64_tr_b16 v[168:169], v180 offset:16896
	ds_read_b64_tr_b16 v[170:171], v180 offset:25344
	ds_read_b64_tr_b16 v[172:173], v180 offset:32
	ds_read_b64_tr_b16 v[174:175], v180 offset:8480
	ds_read_b64_tr_b16 v[176:177], v180 offset:16928
	ds_read_b64_tr_b16 v[178:179], v180 offset:25376
	s_waitcnt lgkmcnt(4)
	v_mfma_f32_16x16x32_bf16 v[4:7], v[0:3], v[148:151], v[4:7]
	v_mfma_f32_16x16x32_bf16 v[68:71], v[0:3], v[206:209], v[68:71]
	v_mfma_f32_16x16x32_bf16 v[4:7], v[168:171], v[152:155], v[4:7]
	v_mfma_f32_16x16x32_bf16 v[68:71], v[168:171], v[224:227], v[68:71]
	ds_read_b64_tr_b16 v[0:1], v180 offset:64
	ds_read_b64_tr_b16 v[2:3], v180 offset:8512
	ds_read_b64_tr_b16 v[168:169], v180 offset:16960
	ds_read_b64_tr_b16 v[170:171], v180 offset:25408
	s_waitcnt lgkmcnt(4)
	v_mfma_f32_16x16x32_bf16 v[8:11], v[172:175], v[148:151], v[8:11]
	v_mfma_f32_16x16x32_bf16 v[72:75], v[172:175], v[206:209], v[72:75]
	v_mfma_f32_16x16x32_bf16 v[8:11], v[176:179], v[152:155], v[8:11]
	v_mfma_f32_16x16x32_bf16 v[72:75], v[176:179], v[224:227], v[72:75]
	ds_read_b64_tr_b16 v[172:173], v180 offset:96
	ds_read_b64_tr_b16 v[174:175], v180 offset:8544
	ds_read_b64_tr_b16 v[176:177], v180 offset:16992
	ds_read_b64_tr_b16 v[178:179], v180 offset:25440
	s_waitcnt lgkmcnt(4)
	v_mfma_f32_16x16x32_bf16 v[12:15], v[0:3], v[148:151], v[12:15]
	v_mfma_f32_16x16x32_bf16 v[76:79], v[0:3], v[206:209], v[76:79]
	v_mfma_f32_16x16x32_bf16 v[12:15], v[168:171], v[152:155], v[12:15]
	v_mfma_f32_16x16x32_bf16 v[76:79], v[168:171], v[224:227], v[76:79]
	ds_read_b64_tr_b16 v[0:1], v180 offset:128
	ds_read_b64_tr_b16 v[2:3], v180 offset:8576
	ds_read_b64_tr_b16 v[168:169], v180 offset:17024
	ds_read_b64_tr_b16 v[170:171], v180 offset:25472
	s_waitcnt lgkmcnt(4)
	v_mfma_f32_16x16x32_bf16 v[16:19], v[172:175], v[148:151], v[16:19]
	v_mfma_f32_16x16x32_bf16 v[80:83], v[172:175], v[206:209], v[80:83]
	v_mfma_f32_16x16x32_bf16 v[16:19], v[176:179], v[152:155], v[16:19]
	v_mfma_f32_16x16x32_bf16 v[80:83], v[176:179], v[224:227], v[80:83]
	ds_read_b64_tr_b16 v[172:173], v180 offset:160
	ds_read_b64_tr_b16 v[174:175], v180 offset:8608
	ds_read_b64_tr_b16 v[176:177], v180 offset:17056
	ds_read_b64_tr_b16 v[178:179], v180 offset:25504
	s_waitcnt lgkmcnt(4)
	v_mfma_f32_16x16x32_bf16 v[20:23], v[0:3], v[148:151], v[20:23]
	v_mfma_f32_16x16x32_bf16 v[84:87], v[0:3], v[206:209], v[84:87]
	v_mfma_f32_16x16x32_bf16 v[20:23], v[168:171], v[152:155], v[20:23]
	v_mfma_f32_16x16x32_bf16 v[84:87], v[168:171], v[224:227], v[84:87]
	ds_read_b64_tr_b16 v[0:1], v180 offset:192
	ds_read_b64_tr_b16 v[2:3], v180 offset:8640
	ds_read_b64_tr_b16 v[168:169], v180 offset:17088
	ds_read_b64_tr_b16 v[170:171], v180 offset:25536
	s_waitcnt lgkmcnt(4)
	v_mfma_f32_16x16x32_bf16 v[24:27], v[172:175], v[148:151], v[24:27]
	v_mfma_f32_16x16x32_bf16 v[88:91], v[172:175], v[206:209], v[88:91]
	v_mfma_f32_16x16x32_bf16 v[24:27], v[176:179], v[152:155], v[24:27]
	v_mfma_f32_16x16x32_bf16 v[88:91], v[176:179], v[224:227], v[88:91]
	ds_read_b64_tr_b16 v[172:173], v180 offset:224
	ds_read_b64_tr_b16 v[174:175], v180 offset:8672
	ds_read_b64_tr_b16 v[176:177], v180 offset:17120
	ds_read_b64_tr_b16 v[178:179], v180 offset:25568
	s_waitcnt lgkmcnt(4)
	v_mfma_f32_16x16x32_bf16 v[28:31], v[0:3], v[148:151], v[28:31]
	v_mfma_f32_16x16x32_bf16 v[92:95], v[0:3], v[206:209], v[92:95]
	v_mfma_f32_16x16x32_bf16 v[28:31], v[168:171], v[152:155], v[28:31]
	v_mfma_f32_16x16x32_bf16 v[92:95], v[168:171], v[224:227], v[92:95]
	ds_read_b64_tr_b16 v[0:1], v180 offset:256
	ds_read_b64_tr_b16 v[2:3], v180 offset:8704
	ds_read_b64_tr_b16 v[168:169], v180 offset:17152
	ds_read_b64_tr_b16 v[170:171], v180 offset:25600
	s_waitcnt lgkmcnt(4)
	v_mfma_f32_16x16x32_bf16 v[32:35], v[172:175], v[148:151], v[32:35]
	v_mfma_f32_16x16x32_bf16 v[96:99], v[172:175], v[206:209], v[96:99]
	v_mfma_f32_16x16x32_bf16 v[32:35], v[176:179], v[152:155], v[32:35]
	v_mfma_f32_16x16x32_bf16 v[96:99], v[176:179], v[224:227], v[96:99]
	ds_read_b64_tr_b16 v[172:173], v180 offset:288
	ds_read_b64_tr_b16 v[174:175], v180 offset:8736
	ds_read_b64_tr_b16 v[176:177], v180 offset:17184
	ds_read_b64_tr_b16 v[178:179], v180 offset:25632
	s_waitcnt lgkmcnt(4)
	v_mfma_f32_16x16x32_bf16 v[36:39], v[0:3], v[148:151], v[36:39]
	v_mfma_f32_16x16x32_bf16 v[100:103], v[0:3], v[206:209], v[100:103]
	v_mfma_f32_16x16x32_bf16 v[36:39], v[168:171], v[152:155], v[36:39]
	v_mfma_f32_16x16x32_bf16 v[100:103], v[168:171], v[224:227], v[100:103]
	ds_read_b64_tr_b16 v[0:1], v180 offset:320
	ds_read_b64_tr_b16 v[2:3], v180 offset:8768
	ds_read_b64_tr_b16 v[168:169], v180 offset:17216
	ds_read_b64_tr_b16 v[170:171], v180 offset:25664
	s_waitcnt lgkmcnt(4)
	v_mfma_f32_16x16x32_bf16 v[40:43], v[172:175], v[148:151], v[40:43]
	v_mfma_f32_16x16x32_bf16 v[104:107], v[172:175], v[206:209], v[104:107]
	v_mfma_f32_16x16x32_bf16 v[40:43], v[176:179], v[152:155], v[40:43]
	v_mfma_f32_16x16x32_bf16 v[104:107], v[176:179], v[224:227], v[104:107]
	ds_read_b64_tr_b16 v[172:173], v180 offset:352
	ds_read_b64_tr_b16 v[174:175], v180 offset:8800
	ds_read_b64_tr_b16 v[176:177], v180 offset:17248
	ds_read_b64_tr_b16 v[178:179], v180 offset:25696
	s_waitcnt lgkmcnt(4)
	v_mfma_f32_16x16x32_bf16 v[44:47], v[0:3], v[148:151], v[44:47]
	v_mfma_f32_16x16x32_bf16 v[108:111], v[0:3], v[206:209], v[108:111]
	v_mfma_f32_16x16x32_bf16 v[44:47], v[168:171], v[152:155], v[44:47]
	v_mfma_f32_16x16x32_bf16 v[108:111], v[168:171], v[224:227], v[108:111]
	ds_read_b64_tr_b16 v[0:1], v180 offset:384
	ds_read_b64_tr_b16 v[2:3], v180 offset:8832
	ds_read_b64_tr_b16 v[168:169], v180 offset:17280
	ds_read_b64_tr_b16 v[170:171], v180 offset:25728
	s_waitcnt lgkmcnt(4)
	v_mfma_f32_16x16x32_bf16 v[48:51], v[172:175], v[148:151], v[48:51]
	v_mfma_f32_16x16x32_bf16 v[112:115], v[172:175], v[206:209], v[112:115]
	v_mfma_f32_16x16x32_bf16 v[48:51], v[176:179], v[152:155], v[48:51]
	v_mfma_f32_16x16x32_bf16 v[112:115], v[176:179], v[224:227], v[112:115]
	ds_read_b64_tr_b16 v[172:173], v180 offset:416
	ds_read_b64_tr_b16 v[174:175], v180 offset:8864
	ds_read_b64_tr_b16 v[176:177], v180 offset:17312
	ds_read_b64_tr_b16 v[178:179], v180 offset:25760
	s_waitcnt lgkmcnt(4)
	v_mfma_f32_16x16x32_bf16 v[52:55], v[0:3], v[148:151], v[52:55]
	v_mfma_f32_16x16x32_bf16 v[116:119], v[0:3], v[206:209], v[116:119]
	v_mfma_f32_16x16x32_bf16 v[52:55], v[168:171], v[152:155], v[52:55]
	v_mfma_f32_16x16x32_bf16 v[116:119], v[168:171], v[224:227], v[116:119]
	ds_read_b64_tr_b16 v[0:1], v180 offset:448
	ds_read_b64_tr_b16 v[2:3], v180 offset:8896
	ds_read_b64_tr_b16 v[168:169], v180 offset:17344
	ds_read_b64_tr_b16 v[170:171], v180 offset:25792
	s_waitcnt lgkmcnt(4)
	v_mfma_f32_16x16x32_bf16 v[56:59], v[172:175], v[148:151], v[56:59]
	v_mfma_f32_16x16x32_bf16 v[120:123], v[172:175], v[206:209], v[120:123]
	v_mfma_f32_16x16x32_bf16 v[56:59], v[176:179], v[152:155], v[56:59]
	v_mfma_f32_16x16x32_bf16 v[120:123], v[176:179], v[224:227], v[120:123]
	ds_read_b64_tr_b16 v[172:173], v180 offset:480
	ds_read_b64_tr_b16 v[174:175], v180 offset:8928
	ds_read_b64_tr_b16 v[176:177], v180 offset:17376
	ds_read_b64_tr_b16 v[178:179], v180 offset:25824
	s_waitcnt lgkmcnt(4)
	v_mfma_f32_16x16x32_bf16 v[60:63], v[0:3], v[148:151], v[60:63]
	v_mfma_f32_16x16x32_bf16 v[124:127], v[0:3], v[206:209], v[124:127]
	v_mfma_f32_16x16x32_bf16 v[60:63], v[168:171], v[152:155], v[60:63]
	v_mfma_f32_16x16x32_bf16 v[124:127], v[168:171], v[224:227], v[124:127]
	s_waitcnt lgkmcnt(0)
	v_mfma_f32_16x16x32_bf16 v[64:67], v[172:175], v[148:151], v[64:67]
	v_mfma_f32_16x16x32_bf16 v[128:131], v[172:175], v[206:209], v[128:131]
	v_mfma_f32_16x16x32_bf16 v[64:67], v[176:179], v[152:155], v[64:67]
	v_mfma_f32_16x16x32_bf16 v[128:131], v[176:179], v[224:227], v[128:131]
	s_waitcnt vmcnt(0)
	ds_write_b128 v187, v[236:239] offset:33792
	ds_write_b128 v187, v[240:243] offset:33920
	ds_write_b128 v187, v[164:167] offset:34048
	ds_write_b128 v187, v[182:185] offset:34176
	s_waitcnt lgkmcnt(0)
	s_barrier
	ds_read_b64_tr_b16 v[0:1], v180 offset:33792
	ds_read_b64_tr_b16 v[2:3], v180 offset:42240
	ds_read_b64_tr_b16 v[168:169], v180 offset:50688
	ds_read_b64_tr_b16 v[170:171], v180 offset:59136
	ds_read_b64_tr_b16 v[172:173], v180 offset:33824
	ds_read_b64_tr_b16 v[174:175], v180 offset:42272
	ds_read_b64_tr_b16 v[176:177], v180 offset:50720
	ds_read_b64_tr_b16 v[178:179], v180 offset:59168
	s_waitcnt lgkmcnt(4)
	v_mfma_f32_16x16x32_bf16 v[4:7], v[0:3], v[156:159], v[4:7]
	v_mfma_f32_16x16x32_bf16 v[68:71], v[0:3], v[228:231], v[68:71]
	v_mfma_f32_16x16x32_bf16 v[4:7], v[168:171], v[160:163], v[4:7]
	v_mfma_f32_16x16x32_bf16 v[68:71], v[168:171], v[232:235], v[68:71]
	ds_read_b64_tr_b16 v[0:1], v180 offset:33856
	ds_read_b64_tr_b16 v[2:3], v180 offset:42304
	ds_read_b64_tr_b16 v[168:169], v180 offset:50752
	ds_read_b64_tr_b16 v[170:171], v180 offset:59200
	s_waitcnt lgkmcnt(4)
	v_mfma_f32_16x16x32_bf16 v[8:11], v[172:175], v[156:159], v[8:11]
	v_mfma_f32_16x16x32_bf16 v[72:75], v[172:175], v[228:231], v[72:75]
	v_mfma_f32_16x16x32_bf16 v[8:11], v[176:179], v[160:163], v[8:11]
	v_mfma_f32_16x16x32_bf16 v[72:75], v[176:179], v[232:235], v[72:75]
	ds_read_b64_tr_b16 v[172:173], v180 offset:33888
	ds_read_b64_tr_b16 v[174:175], v180 offset:42336
	ds_read_b64_tr_b16 v[176:177], v180 offset:50784
	ds_read_b64_tr_b16 v[178:179], v180 offset:59232
	s_waitcnt lgkmcnt(4)
	v_mfma_f32_16x16x32_bf16 v[12:15], v[0:3], v[156:159], v[12:15]
	v_mfma_f32_16x16x32_bf16 v[76:79], v[0:3], v[228:231], v[76:79]
	v_mfma_f32_16x16x32_bf16 v[12:15], v[168:171], v[160:163], v[12:15]
	v_mfma_f32_16x16x32_bf16 v[76:79], v[168:171], v[232:235], v[76:79]
	ds_read_b64_tr_b16 v[0:1], v180 offset:33920
	ds_read_b64_tr_b16 v[2:3], v180 offset:42368
	ds_read_b64_tr_b16 v[168:169], v180 offset:50816
	ds_read_b64_tr_b16 v[170:171], v180 offset:59264
	s_waitcnt lgkmcnt(4)
	v_mfma_f32_16x16x32_bf16 v[16:19], v[172:175], v[156:159], v[16:19]
	v_mfma_f32_16x16x32_bf16 v[80:83], v[172:175], v[228:231], v[80:83]
	v_mfma_f32_16x16x32_bf16 v[16:19], v[176:179], v[160:163], v[16:19]
	v_mfma_f32_16x16x32_bf16 v[80:83], v[176:179], v[232:235], v[80:83]
	ds_read_b64_tr_b16 v[172:173], v180 offset:33952
	ds_read_b64_tr_b16 v[174:175], v180 offset:42400
	ds_read_b64_tr_b16 v[176:177], v180 offset:50848
	ds_read_b64_tr_b16 v[178:179], v180 offset:59296
	s_waitcnt lgkmcnt(4)
	v_mfma_f32_16x16x32_bf16 v[20:23], v[0:3], v[156:159], v[20:23]
	v_mfma_f32_16x16x32_bf16 v[84:87], v[0:3], v[228:231], v[84:87]
	v_mfma_f32_16x16x32_bf16 v[20:23], v[168:171], v[160:163], v[20:23]
	v_mfma_f32_16x16x32_bf16 v[84:87], v[168:171], v[232:235], v[84:87]
	ds_read_b64_tr_b16 v[0:1], v180 offset:33984
	ds_read_b64_tr_b16 v[2:3], v180 offset:42432
	ds_read_b64_tr_b16 v[168:169], v180 offset:50880
	ds_read_b64_tr_b16 v[170:171], v180 offset:59328
	s_waitcnt lgkmcnt(4)
	v_mfma_f32_16x16x32_bf16 v[24:27], v[172:175], v[156:159], v[24:27]
	v_mfma_f32_16x16x32_bf16 v[88:91], v[172:175], v[228:231], v[88:91]
	v_mfma_f32_16x16x32_bf16 v[24:27], v[176:179], v[160:163], v[24:27]
	v_mfma_f32_16x16x32_bf16 v[88:91], v[176:179], v[232:235], v[88:91]
	ds_read_b64_tr_b16 v[172:173], v180 offset:34016
	ds_read_b64_tr_b16 v[174:175], v180 offset:42464
	ds_read_b64_tr_b16 v[176:177], v180 offset:50912
	ds_read_b64_tr_b16 v[178:179], v180 offset:59360
	s_waitcnt lgkmcnt(4)
	v_mfma_f32_16x16x32_bf16 v[28:31], v[0:3], v[156:159], v[28:31]
	v_mfma_f32_16x16x32_bf16 v[92:95], v[0:3], v[228:231], v[92:95]
	v_mfma_f32_16x16x32_bf16 v[28:31], v[168:171], v[160:163], v[28:31]
	v_mfma_f32_16x16x32_bf16 v[92:95], v[168:171], v[232:235], v[92:95]
	ds_read_b64_tr_b16 v[0:1], v180 offset:34048
	ds_read_b64_tr_b16 v[2:3], v180 offset:42496
	ds_read_b64_tr_b16 v[168:169], v180 offset:50944
	ds_read_b64_tr_b16 v[170:171], v180 offset:59392
	s_waitcnt lgkmcnt(4)
	v_mfma_f32_16x16x32_bf16 v[32:35], v[172:175], v[156:159], v[32:35]
	v_mfma_f32_16x16x32_bf16 v[96:99], v[172:175], v[228:231], v[96:99]
	v_mfma_f32_16x16x32_bf16 v[32:35], v[176:179], v[160:163], v[32:35]
	v_mfma_f32_16x16x32_bf16 v[96:99], v[176:179], v[232:235], v[96:99]
	ds_read_b64_tr_b16 v[172:173], v180 offset:34080
	ds_read_b64_tr_b16 v[174:175], v180 offset:42528
	ds_read_b64_tr_b16 v[176:177], v180 offset:50976
	ds_read_b64_tr_b16 v[178:179], v180 offset:59424
	s_waitcnt lgkmcnt(4)
	v_mfma_f32_16x16x32_bf16 v[36:39], v[0:3], v[156:159], v[36:39]
	v_mfma_f32_16x16x32_bf16 v[100:103], v[0:3], v[228:231], v[100:103]
	v_mfma_f32_16x16x32_bf16 v[36:39], v[168:171], v[160:163], v[36:39]
	v_mfma_f32_16x16x32_bf16 v[100:103], v[168:171], v[232:235], v[100:103]
	ds_read_b64_tr_b16 v[0:1], v180 offset:34112
	ds_read_b64_tr_b16 v[2:3], v180 offset:42560
	ds_read_b64_tr_b16 v[168:169], v180 offset:51008
	ds_read_b64_tr_b16 v[170:171], v180 offset:59456
	s_waitcnt lgkmcnt(4)
	v_mfma_f32_16x16x32_bf16 v[40:43], v[172:175], v[156:159], v[40:43]
	v_mfma_f32_16x16x32_bf16 v[104:107], v[172:175], v[228:231], v[104:107]
	v_mfma_f32_16x16x32_bf16 v[40:43], v[176:179], v[160:163], v[40:43]
	v_mfma_f32_16x16x32_bf16 v[104:107], v[176:179], v[232:235], v[104:107]
	ds_read_b64_tr_b16 v[172:173], v180 offset:34144
	ds_read_b64_tr_b16 v[174:175], v180 offset:42592
	ds_read_b64_tr_b16 v[176:177], v180 offset:51040
	ds_read_b64_tr_b16 v[178:179], v180 offset:59488
	s_waitcnt lgkmcnt(4)
	v_mfma_f32_16x16x32_bf16 v[44:47], v[0:3], v[156:159], v[44:47]
	v_mfma_f32_16x16x32_bf16 v[108:111], v[0:3], v[228:231], v[108:111]
	v_mfma_f32_16x16x32_bf16 v[44:47], v[168:171], v[160:163], v[44:47]
	v_mfma_f32_16x16x32_bf16 v[108:111], v[168:171], v[232:235], v[108:111]
	ds_read_b64_tr_b16 v[0:1], v180 offset:34176
	ds_read_b64_tr_b16 v[2:3], v180 offset:42624
	ds_read_b64_tr_b16 v[168:169], v180 offset:51072
	ds_read_b64_tr_b16 v[170:171], v180 offset:59520
	s_waitcnt lgkmcnt(4)
	v_mfma_f32_16x16x32_bf16 v[48:51], v[172:175], v[156:159], v[48:51]
	v_mfma_f32_16x16x32_bf16 v[112:115], v[172:175], v[228:231], v[112:115]
	v_mfma_f32_16x16x32_bf16 v[48:51], v[176:179], v[160:163], v[48:51]
	v_mfma_f32_16x16x32_bf16 v[112:115], v[176:179], v[232:235], v[112:115]
	ds_read_b64_tr_b16 v[172:173], v180 offset:34208
	ds_read_b64_tr_b16 v[174:175], v180 offset:42656
	ds_read_b64_tr_b16 v[176:177], v180 offset:51104
	ds_read_b64_tr_b16 v[178:179], v180 offset:59552
	s_waitcnt lgkmcnt(4)
	v_mfma_f32_16x16x32_bf16 v[52:55], v[0:3], v[156:159], v[52:55]
	v_mfma_f32_16x16x32_bf16 v[116:119], v[0:3], v[228:231], v[116:119]
	v_mfma_f32_16x16x32_bf16 v[52:55], v[168:171], v[160:163], v[52:55]
	v_mfma_f32_16x16x32_bf16 v[116:119], v[168:171], v[232:235], v[116:119]
	ds_read_b64_tr_b16 v[0:1], v180 offset:34240
	ds_read_b64_tr_b16 v[2:3], v180 offset:42688
	ds_read_b64_tr_b16 v[168:169], v180 offset:51136
	ds_read_b64_tr_b16 v[170:171], v180 offset:59584
	s_waitcnt lgkmcnt(4)
	v_mfma_f32_16x16x32_bf16 v[56:59], v[172:175], v[156:159], v[56:59]
	v_mfma_f32_16x16x32_bf16 v[120:123], v[172:175], v[228:231], v[120:123]
	v_mfma_f32_16x16x32_bf16 v[56:59], v[176:179], v[160:163], v[56:59]
	v_mfma_f32_16x16x32_bf16 v[120:123], v[176:179], v[232:235], v[120:123]
	ds_read_b64_tr_b16 v[172:173], v180 offset:34272
	ds_read_b64_tr_b16 v[174:175], v180 offset:42720
	ds_read_b64_tr_b16 v[176:177], v180 offset:51168
	ds_read_b64_tr_b16 v[178:179], v180 offset:59616
	s_waitcnt lgkmcnt(4)
	v_mfma_f32_16x16x32_bf16 v[60:63], v[0:3], v[156:159], v[60:63]
	v_mfma_f32_16x16x32_bf16 v[124:127], v[0:3], v[228:231], v[124:127]
	v_mfma_f32_16x16x32_bf16 v[60:63], v[168:171], v[160:163], v[60:63]
	v_mfma_f32_16x16x32_bf16 v[124:127], v[168:171], v[232:235], v[124:127]
	s_waitcnt lgkmcnt(0)
	v_mfma_f32_16x16x32_bf16 v[64:67], v[172:175], v[156:159], v[64:67]
	v_mfma_f32_16x16x32_bf16 v[128:131], v[172:175], v[228:231], v[128:131]
	v_mfma_f32_16x16x32_bf16 v[64:67], v[176:179], v[160:163], v[64:67]
	v_mfma_f32_16x16x32_bf16 v[128:131], v[176:179], v[232:235], v[128:131]
	s_nop 7
	s_nop 1
	v_lshrrev_b32_e32 v176, 6, v217
	v_and_b32_e32 v177, 15, v217
	v_lshl_add_u32 v176, v176, 4, v177
	v_add_u32_e32 v176, s14, v176
	v_mov_b32_e32 v177, 0
	v_lshlrev_b64 v[172:173], 11, v[176:177]
	v_readlane_b32 s12, v253, 35
	v_readlane_b32 s13, v253, 36
	s_add_u32 s10, s12, s10
	s_addc_u32 s11, s13, s11
	v_lshl_add_u64 v[172:173], s[10:11], 0, v[172:173]
	v_mov_b32_e32 v178, 0xa00000
	v_mad_i64_i32 v[172:173], s[12:13], s6, v178, v[172:173]
	v_lshl_add_u64 v[172:173], v[172:173], 0, s[8:9]
	v_bfe_u32 v176, v217, 4, 2
	v_lshlrev_b32_e32 v176, 3, v176
	v_lshl_add_u64 v[172:173], v[172:173], 0, v[176:177]
	v_mov_b32_e32 v176, 0x40000
	v_lshl_add_u64 v[174:175], v[172:173], 0, v[176:177]
	v_div_scale_f32 v0, s[12:13], v220, v220, 1.0
	v_rcp_f32_e32 v1, v0
	s_nop 0
	v_fma_f32 v2, -v0, v1, 1.0
	v_fmac_f32_e32 v1, v2, v1
	v_div_scale_f32 v2, vcc, 1.0, v220, 1.0
	v_mul_f32_e32 v3, v2, v1
	v_fma_f32 v168, -v0, v3, v2
	v_fmac_f32_e32 v3, v168, v1
	v_fma_f32 v0, -v0, v3, v2
	v_div_fmas_f32 v0, v0, v1, v3
	v_div_fixup_f32 v178, v0, v220, 1.0
	v_div_scale_f32 v0, s[12:13], v221, v221, 1.0
	v_rcp_f32_e32 v1, v0
	s_nop 0
	v_fma_f32 v2, -v0, v1, 1.0
	v_fmac_f32_e32 v1, v2, v1
	v_div_scale_f32 v2, vcc, 1.0, v221, 1.0
	v_mul_f32_e32 v3, v2, v1
	v_fma_f32 v168, -v0, v3, v2
	v_fmac_f32_e32 v3, v168, v1
	v_fma_f32 v0, -v0, v3, v2
	v_div_fmas_f32 v0, v0, v1, v3
	v_div_fixup_f32 v179, v0, v221, 1.0
	v_mul_f32_e32 v4, v178, v4
	v_mul_f32_e32 v5, v178, v5
	v_mul_f32_e32 v6, v178, v6
	v_mul_f32_e32 v7, v178, v7
	v_cvt_pk_bf16_f32 v236, v4, v5
	v_cvt_pk_bf16_f32 v237, v6, v7
	global_store_dwordx2 v[172:173], v[236:237], off
	v_mul_f32_e32 v8, v178, v8
	v_mul_f32_e32 v9, v178, v9
	v_mul_f32_e32 v10, v178, v10
	v_mul_f32_e32 v11, v178, v11
	v_cvt_pk_bf16_f32 v238, v8, v9
	v_cvt_pk_bf16_f32 v239, v10, v11
	global_store_dwordx2 v[172:173], v[238:239], off offset:32
	v_mul_f32_e32 v12, v178, v12
	v_mul_f32_e32 v13, v178, v13
	v_mul_f32_e32 v14, v178, v14
	v_mul_f32_e32 v15, v178, v15
	v_cvt_pk_bf16_f32 v240, v12, v13
	v_cvt_pk_bf16_f32 v241, v14, v15
	global_store_dwordx2 v[172:173], v[240:241], off offset:64
	v_mul_f32_e32 v16, v178, v16
	v_mul_f32_e32 v17, v178, v17
	v_mul_f32_e32 v18, v178, v18
	v_mul_f32_e32 v19, v178, v19
	v_cvt_pk_bf16_f32 v242, v16, v17
	v_cvt_pk_bf16_f32 v243, v18, v19
	global_store_dwordx2 v[172:173], v[242:243], off offset:96
	v_mul_f32_e32 v20, v178, v20
	v_mul_f32_e32 v21, v178, v21
	v_mul_f32_e32 v22, v178, v22
	v_mul_f32_e32 v23, v178, v23
	v_cvt_pk_bf16_f32 v164, v20, v21
	v_cvt_pk_bf16_f32 v165, v22, v23
	global_store_dwordx2 v[172:173], v[164:165], off offset:128
	v_mul_f32_e32 v24, v178, v24
	v_mul_f32_e32 v25, v178, v25
	v_mul_f32_e32 v26, v178, v26
	v_mul_f32_e32 v27, v178, v27
	v_cvt_pk_bf16_f32 v166, v24, v25
	v_cvt_pk_bf16_f32 v167, v26, v27
	global_store_dwordx2 v[172:173], v[166:167], off offset:160
	v_mul_f32_e32 v28, v178, v28
	v_mul_f32_e32 v29, v178, v29
	v_mul_f32_e32 v30, v178, v30
	v_mul_f32_e32 v31, v178, v31
	v_cvt_pk_bf16_f32 v182, v28, v29
	v_cvt_pk_bf16_f32 v183, v30, v31
	global_store_dwordx2 v[172:173], v[182:183], off offset:192
	v_mul_f32_e32 v32, v178, v32
	v_mul_f32_e32 v33, v178, v33
	v_mul_f32_e32 v34, v178, v34
	v_mul_f32_e32 v35, v178, v35
	v_cvt_pk_bf16_f32 v184, v32, v33
	v_cvt_pk_bf16_f32 v185, v34, v35
	global_store_dwordx2 v[172:173], v[184:185], off offset:224
	v_mul_f32_e32 v36, v178, v36
	v_mul_f32_e32 v37, v178, v37
	v_mul_f32_e32 v38, v178, v38
	v_mul_f32_e32 v39, v178, v39
	v_cvt_pk_bf16_f32 v236, v36, v37
	v_cvt_pk_bf16_f32 v237, v38, v39
	global_store_dwordx2 v[172:173], v[236:237], off offset:256
	v_mul_f32_e32 v40, v178, v40
	v_mul_f32_e32 v41, v178, v41
	v_mul_f32_e32 v42, v178, v42
	v_mul_f32_e32 v43, v178, v43
	v_cvt_pk_bf16_f32 v238, v40, v41
	v_cvt_pk_bf16_f32 v239, v42, v43
	global_store_dwordx2 v[172:173], v[238:239], off offset:288
	v_mul_f32_e32 v44, v178, v44
	v_mul_f32_e32 v45, v178, v45
	v_mul_f32_e32 v46, v178, v46
	v_mul_f32_e32 v47, v178, v47
	v_cvt_pk_bf16_f32 v240, v44, v45
	v_cvt_pk_bf16_f32 v241, v46, v47
	global_store_dwordx2 v[172:173], v[240:241], off offset:320
	v_mul_f32_e32 v48, v178, v48
	v_mul_f32_e32 v49, v178, v49
	v_mul_f32_e32 v50, v178, v50
	v_mul_f32_e32 v51, v178, v51
	v_cvt_pk_bf16_f32 v242, v48, v49
	v_cvt_pk_bf16_f32 v243, v50, v51
	global_store_dwordx2 v[172:173], v[242:243], off offset:352
	v_mul_f32_e32 v52, v178, v52
	v_mul_f32_e32 v53, v178, v53
	v_mul_f32_e32 v54, v178, v54
	v_mul_f32_e32 v55, v178, v55
	v_cvt_pk_bf16_f32 v164, v52, v53
	v_cvt_pk_bf16_f32 v165, v54, v55
	global_store_dwordx2 v[172:173], v[164:165], off offset:384
	v_mul_f32_e32 v56, v178, v56
	v_mul_f32_e32 v57, v178, v57
	v_mul_f32_e32 v58, v178, v58
	v_mul_f32_e32 v59, v178, v59
	v_cvt_pk_bf16_f32 v166, v56, v57
	v_cvt_pk_bf16_f32 v167, v58, v59
	global_store_dwordx2 v[172:173], v[166:167], off offset:416
	v_mul_f32_e32 v60, v178, v60
	v_mul_f32_e32 v61, v178, v61
	v_mul_f32_e32 v62, v178, v62
	v_mul_f32_e32 v63, v178, v63
	v_cvt_pk_bf16_f32 v182, v60, v61
	v_cvt_pk_bf16_f32 v183, v62, v63
	global_store_dwordx2 v[172:173], v[182:183], off offset:448
	v_mul_f32_e32 v64, v178, v64
	v_mul_f32_e32 v65, v178, v65
	v_mul_f32_e32 v66, v178, v66
	v_mul_f32_e32 v67, v178, v67
	v_cvt_pk_bf16_f32 v184, v64, v65
	v_cvt_pk_bf16_f32 v185, v66, v67
	global_store_dwordx2 v[172:173], v[184:185], off offset:480
	v_mul_f32_e32 v68, v179, v68
	v_mul_f32_e32 v69, v179, v69
	v_mul_f32_e32 v70, v179, v70
	v_mul_f32_e32 v71, v179, v71
	v_cvt_pk_bf16_f32 v236, v68, v69
	v_cvt_pk_bf16_f32 v237, v70, v71
	global_store_dwordx2 v[174:175], v[236:237], off
	v_mul_f32_e32 v72, v179, v72
	v_mul_f32_e32 v73, v179, v73
	v_mul_f32_e32 v74, v179, v74
	v_mul_f32_e32 v75, v179, v75
	v_cvt_pk_bf16_f32 v238, v72, v73
	v_cvt_pk_bf16_f32 v239, v74, v75
	global_store_dwordx2 v[174:175], v[238:239], off offset:32
	v_mul_f32_e32 v76, v179, v76
	v_mul_f32_e32 v77, v179, v77
	v_mul_f32_e32 v78, v179, v78
	v_mul_f32_e32 v79, v179, v79
	v_cvt_pk_bf16_f32 v240, v76, v77
	v_cvt_pk_bf16_f32 v241, v78, v79
	global_store_dwordx2 v[174:175], v[240:241], off offset:64
	v_mul_f32_e32 v80, v179, v80
	v_mul_f32_e32 v81, v179, v81
	v_mul_f32_e32 v82, v179, v82
	v_mul_f32_e32 v83, v179, v83
	v_cvt_pk_bf16_f32 v242, v80, v81
	v_cvt_pk_bf16_f32 v243, v82, v83
	global_store_dwordx2 v[174:175], v[242:243], off offset:96
	v_mul_f32_e32 v84, v179, v84
	v_mul_f32_e32 v85, v179, v85
	v_mul_f32_e32 v86, v179, v86
	v_mul_f32_e32 v87, v179, v87
	v_cvt_pk_bf16_f32 v164, v84, v85
	v_cvt_pk_bf16_f32 v165, v86, v87
	global_store_dwordx2 v[174:175], v[164:165], off offset:128
	v_mul_f32_e32 v88, v179, v88
	v_mul_f32_e32 v89, v179, v89
	v_mul_f32_e32 v90, v179, v90
	v_mul_f32_e32 v91, v179, v91
	v_cvt_pk_bf16_f32 v166, v88, v89
	v_cvt_pk_bf16_f32 v167, v90, v91
	global_store_dwordx2 v[174:175], v[166:167], off offset:160
	v_mul_f32_e32 v92, v179, v92
	v_mul_f32_e32 v93, v179, v93
	v_mul_f32_e32 v94, v179, v94
	v_mul_f32_e32 v95, v179, v95
	v_cvt_pk_bf16_f32 v182, v92, v93
	v_cvt_pk_bf16_f32 v183, v94, v95
	global_store_dwordx2 v[174:175], v[182:183], off offset:192
	v_mul_f32_e32 v96, v179, v96
	v_mul_f32_e32 v97, v179, v97
	v_mul_f32_e32 v98, v179, v98
	v_mul_f32_e32 v99, v179, v99
	v_cvt_pk_bf16_f32 v184, v96, v97
	v_cvt_pk_bf16_f32 v185, v98, v99
	global_store_dwordx2 v[174:175], v[184:185], off offset:224
	v_mul_f32_e32 v100, v179, v100
	v_mul_f32_e32 v101, v179, v101
	v_mul_f32_e32 v102, v179, v102
	v_mul_f32_e32 v103, v179, v103
	v_cvt_pk_bf16_f32 v236, v100, v101
	v_cvt_pk_bf16_f32 v237, v102, v103
	global_store_dwordx2 v[174:175], v[236:237], off offset:256
	v_mul_f32_e32 v104, v179, v104
	v_mul_f32_e32 v105, v179, v105
	v_mul_f32_e32 v106, v179, v106
	v_mul_f32_e32 v107, v179, v107
	v_cvt_pk_bf16_f32 v238, v104, v105
	v_cvt_pk_bf16_f32 v239, v106, v107
	global_store_dwordx2 v[174:175], v[238:239], off offset:288
	v_mul_f32_e32 v108, v179, v108
	v_mul_f32_e32 v109, v179, v109
	v_mul_f32_e32 v110, v179, v110
	v_mul_f32_e32 v111, v179, v111
	v_cvt_pk_bf16_f32 v240, v108, v109
	v_cvt_pk_bf16_f32 v241, v110, v111
	global_store_dwordx2 v[174:175], v[240:241], off offset:320
	v_mul_f32_e32 v112, v179, v112
	v_mul_f32_e32 v113, v179, v113
	v_mul_f32_e32 v114, v179, v114
	v_mul_f32_e32 v115, v179, v115
	v_cvt_pk_bf16_f32 v242, v112, v113
	v_cvt_pk_bf16_f32 v243, v114, v115
	global_store_dwordx2 v[174:175], v[242:243], off offset:352
	v_mul_f32_e32 v116, v179, v116
	v_mul_f32_e32 v117, v179, v117
	v_mul_f32_e32 v118, v179, v118
	v_mul_f32_e32 v119, v179, v119
	v_cvt_pk_bf16_f32 v164, v116, v117
	v_cvt_pk_bf16_f32 v165, v118, v119
	global_store_dwordx2 v[174:175], v[164:165], off offset:384
	v_mul_f32_e32 v120, v179, v120
	v_mul_f32_e32 v121, v179, v121
	v_mul_f32_e32 v122, v179, v122
	v_mul_f32_e32 v123, v179, v123
	v_cvt_pk_bf16_f32 v166, v120, v121
	v_cvt_pk_bf16_f32 v167, v122, v123
	global_store_dwordx2 v[174:175], v[166:167], off offset:416
	v_mul_f32_e32 v124, v179, v124
	v_mul_f32_e32 v125, v179, v125
	v_mul_f32_e32 v126, v179, v126
	v_mul_f32_e32 v127, v179, v127
	v_cvt_pk_bf16_f32 v182, v124, v125
	v_cvt_pk_bf16_f32 v183, v126, v127
	global_store_dwordx2 v[174:175], v[182:183], off offset:448
	v_mul_f32_e32 v128, v179, v128
	v_mul_f32_e32 v129, v179, v129
	v_mul_f32_e32 v130, v179, v130
	v_mul_f32_e32 v131, v179, v131
	v_cvt_pk_bf16_f32 v184, v128, v129
	v_cvt_pk_bf16_f32 v185, v130, v131
	global_store_dwordx2 v[174:175], v[184:185], off offset:480
	v_mov_b32_e32 v2, 0x3f803f80
	s_waitcnt lgkmcnt(0)
	s_barrier
